# removed remaining dead waits: 8 duplicate vmcnt(0) in barrier paths, 26 lgkmcnt(0) in the up epilogue with no LDS op outstanding
# baseline (speedup 1.0000x reference)
; __device__ __forceinline__ int otid(int wv) { int t = (wv << 6) | (int)__builtin_amdgcn_mbcnt_hi(~0u, __builtin_amdgcn_mbcnt_lo(~0u, 0u)); asm volatile("" : "+v"(t)); return t; }
; #define PG8_WAIT_V(n) asm volatile("s_waitcnt vmcnt(" #n ")" ::: "memory")
; #define PG8_BAR __builtin_amdgcn_s_barrier()
; template <class Epi, class Sched, bool AREMAP>
; __device__ __forceinline__ void gemm_phase(LAS unsigned char* lds, const Gemm g, const Sched& S, const Epi& E, int wv) {
;     ...
;     PG8_WAIT_V(0);
;     if (wr == 0) PG8_BAR;
;     PG8_BAR;
; __device__ __forceinline__ void grid_bar(unsigned* ctr, unsigned& target, int G, int wv) {
;     asm volatile("s_waitcnt vmcnt(0) lgkmcnt(0)" ::: "memory");
;     __syncthreads();
;     target = (unsigned)__builtin_amdgcn_readfirstlane((int)(target + (unsigned)G));
;     if (otid(wv) == 0) {
;         __builtin_amdgcn_fence(__ATOMIC_RELEASE, "agent");
;         asm volatile("s_waitcnt vmcnt(0)" ::: "memory");
;         __hip_atomic_fetch_add(ctr, 1u, __ATOMIC_RELAXED, __HIP_MEMORY_SCOPE_AGENT);
;         while (__hip_atomic_load(ctr, __ATOMIC_RELAXED, __HIP_MEMORY_SCOPE_AGENT) < target) __builtin_amdgcn_s_sleep(1);
.LBB0_382:
	s_or_b64 exec, exec, s[4:5]
	s_waitcnt lgkmcnt(0)
	s_barrier
	s_setprio 0
	s_waitcnt vmcnt(0) lgkmcnt(0)
	v_mov_b32_e32 v1, v236
	s_barrier
	s_add_i32 s24, s73, s33
	s_nop 0
	v_cmp_eq_u32_e32 vcc, 0, v1
	s_and_saveexec_b64 s[0:1], vcc
	s_cbranch_execz .LBB0_388
	s_mov_b64 s[2:3], exec
	buffer_wbl2 sc1
	s_waitcnt vmcnt(0)
	v_mbcnt_lo_u32_b32 v1, s2, 0
	v_mbcnt_hi_u32_b32 v1, s3, v1
	v_cmp_eq_u32_e32 vcc, 0, v1
	s_and_saveexec_b64 s[4:5], vcc
	s_cbranch_execz .LBB0_385
	s_bcnt1_i32_b64 s2, s[2:3]
	v_mov_b32_e32 v1, s2
	v_readlane_b32 s2, v254, 30
	v_readlane_b32 s3, v254, 31
	s_nop 4
	global_atomic_add v0, v1, s[2:3]

; __device__ __forceinline__ int otid(int wv) { int t = (wv << 6) | (int)__builtin_amdgcn_mbcnt_hi(~0u, __builtin_amdgcn_mbcnt_lo(~0u, 0u)); asm volatile("" : "+v"(t)); return t; }
; __device__ __forceinline__ void grid_bar(unsigned* ctr, unsigned& target, int G, int wv) {
;     asm volatile("s_waitcnt vmcnt(0) lgkmcnt(0)" ::: "memory");
;     __syncthreads();
;     target = (unsigned)__builtin_amdgcn_readfirstlane((int)(target + (unsigned)G));
;     if (otid(wv) == 0) {
;         __builtin_amdgcn_fence(__ATOMIC_RELEASE, "agent");
;         asm volatile("s_waitcnt vmcnt(0)" ::: "memory");
;         __hip_atomic_fetch_add(ctr, 1u, __ATOMIC_RELAXED, __HIP_MEMORY_SCOPE_AGENT);
;         while (__hip_atomic_load(ctr, __ATOMIC_RELAXED, __HIP_MEMORY_SCOPE_AGENT) < target) __builtin_amdgcn_s_sleep(1);
.LBB0_528:
	s_setprio 0
	s_waitcnt vmcnt(0) lgkmcnt(0)
	v_mov_b32_e32 v1, v236
	s_waitcnt lgkmcnt(0)
	s_barrier
	s_add_i32 s10, s24, s33
	s_nop 0
	v_cmp_eq_u32_e32 vcc, 0, v1
	s_and_saveexec_b64 s[0:1], vcc
	s_cbranch_execz .LBB0_534
	s_mov_b64 s[2:3], exec
	buffer_wbl2 sc1
	s_waitcnt vmcnt(0)
	v_mbcnt_lo_u32_b32 v1, s2, 0
	v_mbcnt_hi_u32_b32 v1, s3, v1
	v_cmp_eq_u32_e32 vcc, 0, v1
	s_and_saveexec_b64 s[4:5], vcc
	s_cbranch_execz .LBB0_531
	s_bcnt1_i32_b64 s2, s[2:3]
	v_mov_b32_e32 v1, s2
	v_readlane_b32 s2, v254, 30
	v_readlane_b32 s3, v254, 31
	s_nop 4
	global_atomic_add v0, v1, s[2:3]

; __device__ __forceinline__ int otid(int wv) { int t = (wv << 6) | (int)__builtin_amdgcn_mbcnt_hi(~0u, __builtin_amdgcn_mbcnt_lo(~0u, 0u)); asm volatile("" : "+v"(t)); return t; }
; __device__ __forceinline__ void grid_bar(unsigned* ctr, unsigned& target, int G, int wv) {
;     asm volatile("s_waitcnt vmcnt(0) lgkmcnt(0)" ::: "memory");
;     __syncthreads();
;     target = (unsigned)__builtin_amdgcn_readfirstlane((int)(target + (unsigned)G));
;     if (otid(wv) == 0) {
;         __builtin_amdgcn_fence(__ATOMIC_RELEASE, "agent");
;         asm volatile("s_waitcnt vmcnt(0)" ::: "memory");
;         __hip_atomic_fetch_add(ctr, 1u, __ATOMIC_RELAXED, __HIP_MEMORY_SCOPE_AGENT);
;         while (__hip_atomic_load(ctr, __ATOMIC_RELAXED, __HIP_MEMORY_SCOPE_AGENT) < target) __builtin_amdgcn_s_sleep(1);
.LBB0_590:
	s_setprio 0
	s_waitcnt vmcnt(0) lgkmcnt(0)
	v_mov_b32_e32 v1, v236
	s_waitcnt lgkmcnt(0)
	s_barrier
	s_add_i32 s10, s10, s33
	s_nop 0
	v_cmp_eq_u32_e32 vcc, 0, v1
	s_and_saveexec_b64 s[0:1], vcc
	s_cbranch_execz .LBB0_596
	s_mov_b64 s[2:3], exec
	buffer_wbl2 sc1
	s_waitcnt vmcnt(0)
	v_mbcnt_lo_u32_b32 v1, s2, 0
	v_mbcnt_hi_u32_b32 v1, s3, v1
	v_cmp_eq_u32_e32 vcc, 0, v1
	s_and_saveexec_b64 s[4:5], vcc
	s_cbranch_execz .LBB0_593
	s_bcnt1_i32_b64 s2, s[2:3]
	v_mov_b32_e32 v1, s2
	v_readlane_b32 s2, v254, 30
	v_readlane_b32 s3, v254, 31
	s_nop 4
	global_atomic_add v0, v1, s[2:3]

; __device__ __forceinline__ int otid(int wv) { int t = (wv << 6) | (int)__builtin_amdgcn_mbcnt_hi(~0u, __builtin_amdgcn_mbcnt_lo(~0u, 0u)); asm volatile("" : "+v"(t)); return t; }
; #define PG8_WAIT_V(n) asm volatile("s_waitcnt vmcnt(" #n ")" ::: "memory")
; #define PG8_BAR __builtin_amdgcn_s_barrier()
; template <class Epi, class Sched, bool AREMAP>
; __device__ __forceinline__ void gemm_phase(LAS unsigned char* lds, const Gemm g, const Sched& S, const Epi& E, int wv) {
;     ...
;     PG8_WAIT_V(0);
;     if (wr == 0) PG8_BAR;
;     PG8_BAR;
; __device__ __forceinline__ void grid_bar(unsigned* ctr, unsigned& target, int G, int wv) {
;     asm volatile("s_waitcnt vmcnt(0) lgkmcnt(0)" ::: "memory");
;     __syncthreads();
;     target = (unsigned)__builtin_amdgcn_readfirstlane((int)(target + (unsigned)G));
;     if (otid(wv) == 0) {
;         __builtin_amdgcn_fence(__ATOMIC_RELEASE, "agent");
;         asm volatile("s_waitcnt vmcnt(0)" ::: "memory");
;         __hip_atomic_fetch_add(ctr, 1u, __ATOMIC_RELAXED, __HIP_MEMORY_SCOPE_AGENT);
;         while (__hip_atomic_load(ctr, __ATOMIC_RELAXED, __HIP_MEMORY_SCOPE_AGENT) < target) __builtin_amdgcn_s_sleep(1);
.LBB0_605:
	s_or_b64 exec, exec, s[4:5]
	s_waitcnt lgkmcnt(0)
	s_barrier
	s_setprio 0
	s_waitcnt vmcnt(0) lgkmcnt(0)
	v_mov_b32_e32 v1, v236
	s_barrier
	s_add_i32 s20, s10, s33
	s_nop 0
	v_cmp_eq_u32_e32 vcc, 0, v1
	s_and_saveexec_b64 s[0:1], vcc
	s_cbranch_execz .LBB0_611
	s_mov_b64 s[2:3], exec
	buffer_wbl2 sc1
	s_waitcnt vmcnt(0)
	v_mbcnt_lo_u32_b32 v1, s2, 0
	v_mbcnt_hi_u32_b32 v1, s3, v1
	v_cmp_eq_u32_e32 vcc, 0, v1
	s_and_saveexec_b64 s[4:5], vcc
	s_cbranch_execz .LBB0_608
	s_bcnt1_i32_b64 s2, s[2:3]
	v_mov_b32_e32 v1, s2
	v_readlane_b32 s2, v254, 30
	v_readlane_b32 s3, v254, 31
	s_nop 4
	global_atomic_add v0, v1, s[2:3]

; __device__ __forceinline__ unsigned cvt_pk_bf16(float lo, float hi) { f32x2_t f = {lo, hi}; bf16x2_t v = __builtin_convertvector(f, bf16x2_t); return __builtin_bit_cast(unsigned, v); }
; __device__ __forceinline__ float sigmoidf_(float x) { return __builtin_amdgcn_rcpf(1.0f + __expf(-x)); }
; #define SHI(lane, v, src) shfl_idx(lane, (v), (src))
;     __device__ __forceinline__ void operator()(const f32x4 (&acc)[2][2][4][2], const Unit& u, int wr, int wc, int fr, int fq) const {
;     ...
;             for (int q = 0; q < 8; ++q) {
;                 const int ai = q >> 2, m = q & 3;
;                 const f32x4 av = acc[ai][0][m][n], ag = acc[ai][1][m][n];
;                 f32x4 rv1, rv2, rg1, rg2;
; #pragma unroll
;                 for (int j = 0; j < 4; ++j) { rv1[j] = SHI(lane, av[j], src1); rv2[j] = SHI(lane, av[j], src2); rg1[j] = SHI(lane, ag[j], src1); rg2[j] = SHI(lane, ag[j], src2); }
;                 const f32x4 sv1 = fr >= 1 ? rv1 : pv1, sv2 = fr >= 2 ? rv2 : pv2, sg1 = fr >= 1 ? rg1 : pg1, sg2 = fr >= 2 ? rg2 : pg2;
;                 const f32x4 ov = wv[2] * av + wv[1] * sv1 + wv[0] * sv2;
;                 const f32x4 og = wg[2] * ag + wg[1] * sg1 + wg[0] * sg2;
;                 u32x2 w;
;                 w.x = cvt_pk_bf16(og[0] * sigmoidf_(og[0]) * ov[0], og[1] * sigmoidf_(og[1]) * ov[1]);
;                 w.y = cvt_pk_bf16(og[2] * sigmoidf_(og[2]) * ov[2], og[3] * sigmoidf_(og[3]) * ov[3]);
;                 *(u32x2*)(act + (size_t)(tok0 + q * 16) * DFF + ch) = w;
;                 if (q == 0 && fr < 2) { float* hp = halo + ((size_t)seg * 4 + fr) * NUP + ch; *(f32x4*)hp = av; *(f32x4*)(hp + DFF) = ag; }
;                 if (q == 7 && fr >= 14) { float* hp = halo + ((size_t)seg * 4 + (fr - 12)) * NUP + ch; *(f32x4*)hp = av; *(f32x4*)(hp + DFF) = ag; }
;                 pv1 = rv1; pv2 = rv2; pg1 = rg1; pg2 = rg2;
;             }
.LBB0_622:
	s_or_b64 exec, exec, s[78:79]
	v_mov_b32_dpp v217, v120 row_ror:1 row_mask:0xf bank_mask:0xf
	v_mov_b32_dpp v221, v121 row_ror:1 row_mask:0xf bank_mask:0xf
	v_mov_b32_dpp v211, v114 row_ror:1 row_mask:0xf bank_mask:0xf
	v_mov_b32_dpp v215, v115 row_ror:1 row_mask:0xf bank_mask:0xf
	v_mov_b32_dpp v209, v118 row_ror:1 row_mask:0xf bank_mask:0xf
	v_mov_b32_dpp v213, v119 row_ror:1 row_mask:0xf bank_mask:0xf
	v_mov_b32_dpp v212, v114 row_ror:2 row_mask:0xf bank_mask:0xf
	v_mov_b32_dpp v216, v115 row_ror:2 row_mask:0xf bank_mask:0xf
	v_mov_b32_dpp v219, v116 row_ror:1 row_mask:0xf bank_mask:0xf
	v_mov_b32_dpp v223, v117 row_ror:1 row_mask:0xf bank_mask:0xf
	v_lshl_add_u64 v[124:125], s[76:77], 0, v[164:165]
	s_mov_b32 s33, 0xb000
	v_mov_b32_dpp v220, v116 row_ror:2 row_mask:0xf bank_mask:0xf
	v_mov_b32_dpp v224, v117 row_ror:2 row_mask:0xf bank_mask:0xf
	s_waitcnt lgkmcnt(0)
	v_cndmask_b32_e64 v127, v221, v208, s[0:1]
	v_cndmask_b32_e64 v126, v217, v206, s[0:1]
	v_mad_u64_u32 v[122:123], s[46:47], v124, s33, 0
	v_cndmask_b32_e64 v193, v215, v198, s[0:1]
	v_cndmask_b32_e64 v192, v211, v186, s[0:1]
	v_pk_mul_f32 v[126:127], v[148:149], v[126:127]
	v_mad_i32_i24 v123, v125, s33, v123
	v_mov_b32_dpp v218, v120 row_ror:2 row_mask:0xf bank_mask:0xf
	v_mov_b32_dpp v222, v121 row_ror:2 row_mask:0xf bank_mask:0xf
	v_cndmask_b32_e64 v125, v213, v204, s[0:1]
	v_cndmask_b32_e64 v124, v209, v199, s[0:1]
	v_pk_fma_f32 v[120:121], v[120:121], v[152:153], v[126:127]
	v_pk_mul_f32 v[126:127], v[138:139], v[192:193]
	v_cndmask_b32_e64 v195, v223, v205, s[0:1]
	v_cndmask_b32_e64 v194, v219, v200, s[0:1]
	v_cndmask_b32_e64 v187, v187, v216, s[2:3]
	v_cndmask_b32_e64 v186, v185, v212, s[2:3]
	v_pk_mul_f32 v[124:125], v[146:147], v[124:125]
	v_pk_fma_f32 v[114:115], v[114:115], v[142:143], v[126:127]
	v_mov_b32_dpp v210, v118 row_ror:2 row_mask:0xf bank_mask:0xf
	v_mov_b32_dpp v214, v119 row_ror:2 row_mask:0xf bank_mask:0xf
	v_pk_fma_f32 v[118:119], v[118:119], v[150:151], v[124:125]
	v_pk_mul_f32 v[124:125], v[140:141], v[194:195]
	v_pk_fma_f32 v[114:115], v[130:131], v[186:187], v[114:115]
	v_cndmask_b32_e64 v199, v202, v224, s[2:3]
	v_cndmask_b32_e64 v198, v197, v220, s[2:3]
	v_pk_fma_f32 v[116:117], v[116:117], v[144:145], v[124:125]
	v_mul_f32_e32 v124, 0xbfb8aa3b, v114
	v_mul_f32_e32 v125, 0xbfb8aa3b, v115
	v_exp_f32_e32 v124, v124
	v_exp_f32_e32 v125, v125
	v_pk_fma_f32 v[116:117], v[132:133], v[198:199], v[116:117]
	v_cndmask_b32_e64 v129, v201, v214, s[2:3]
	v_mul_f32_e32 v126, 0xbfb8aa3b, v116
	v_mul_f32_e32 v127, 0xbfb8aa3b, v117
	v_exp_f32_e32 v126, v126
	v_exp_f32_e32 v127, v127
	v_add_f32_e32 v124, 1.0, v124
	v_add_f32_e32 v125, 1.0, v125
	v_rcp_f32_e32 v124, v124
	v_rcp_f32_e32 v125, v125
	v_add_f32_e32 v126, 1.0, v126
	v_add_f32_e32 v127, 1.0, v127
	v_rcp_f32_e32 v126, v126
	v_rcp_f32_e32 v127, v127
	v_cndmask_b32_e64 v128, v196, v210, s[2:3]
	v_pk_fma_f32 v[118:119], v[134:135], v[128:129], v[118:119]
	v_pk_mul_f32 v[114:115], v[114:115], v[124:125]
	v_cndmask_b32_e64 v179, v207, v222, s[2:3]
	v_cndmask_b32_e64 v178, v203, v218, s[2:3]
	v_pk_mul_f32 v[114:115], v[118:119], v[114:115]
	v_pk_fma_f32 v[120:121], v[136:137], v[178:179], v[120:121]
	v_cvt_pk_bf16_f32 v124, v114, v115
	v_pk_mul_f32 v[114:115], v[116:117], v[126:127]
	v_mov_b32_dpp v203, v112 row_ror:1 row_mask:0xf bank_mask:0xf
	v_mov_b32_dpp v207, v113 row_ror:1 row_mask:0xf bank_mask:0xf
	v_pk_mul_f32 v[114:115], v[120:121], v[114:115]
	v_mov_b32_dpp v197, v106 row_ror:1 row_mask:0xf bank_mask:0xf
	v_mov_b32_dpp v201, v107 row_ror:1 row_mask:0xf bank_mask:0xf
	v_cvt_pk_bf16_f32 v125, v114, v115
	v_or_b32_e32 v114, 16, v184
	v_mov_b64_e32 v[116:117], s[20:21]
	s_movk_i32 s33, 0x2c00
	v_mov_b32_dpp v185, v110 row_ror:1 row_mask:0xf bank_mask:0xf
	v_mov_b32_dpp v199, v111 row_ror:1 row_mask:0xf bank_mask:0xf
	v_mad_i64_i32 v[114:115], s[46:47], v114, s33, v[116:117]
	v_lshlrev_b64 v[118:119], 1, v[170:171]
	v_mov_b32_dpp v198, v106 row_ror:2 row_mask:0xf bank_mask:0xf
	v_mov_b32_dpp v202, v107 row_ror:2 row_mask:0xf bank_mask:0xf
	v_mov_b32_dpp v205, v108 row_ror:1 row_mask:0xf bank_mask:0xf
	v_mov_b32_dpp v225, v109 row_ror:1 row_mask:0xf bank_mask:0xf
	v_lshl_add_u64 v[114:115], v[114:115], 0, v[118:119]
	global_store_dwordx2 v[114:115], v[124:125], off
	v_mov_b32_dpp v206, v108 row_ror:2 row_mask:0xf bank_mask:0xf
	v_mov_b32_dpp v226, v109 row_ror:2 row_mask:0xf bank_mask:0xf
	v_cndmask_b32_e64 v125, v207, v221, s[0:1]
	v_cndmask_b32_e64 v124, v203, v217, s[0:1]
	v_cndmask_b32_e64 v179, v201, v215, s[0:1]
	v_cndmask_b32_e64 v178, v197, v211, s[0:1]
	v_pk_mul_f32 v[124:125], v[148:149], v[124:125]
	v_mov_b32_dpp v204, v112 row_ror:2 row_mask:0xf bank_mask:0xf
	v_mov_b32_dpp v208, v113 row_ror:2 row_mask:0xf bank_mask:0xf
	v_cndmask_b32_e64 v121, v199, v213, s[0:1]
	v_cndmask_b32_e64 v120, v185, v209, s[0:1]
	v_pk_fma_f32 v[112:113], v[112:113], v[152:153], v[124:125]
	v_pk_mul_f32 v[124:125], v[138:139], v[178:179]
	v_cndmask_b32_e64 v187, v225, v223, s[0:1]
	v_cndmask_b32_e64 v186, v205, v219, s[0:1]
	v_cndmask_b32_e64 v193, v216, v202, s[2:3]
	v_cndmask_b32_e64 v192, v212, v198, s[2:3]
	v_pk_mul_f32 v[120:121], v[146:147], v[120:121]
	v_pk_fma_f32 v[106:107], v[106:107], v[142:143], v[124:125]
	v_mov_b32_dpp v196, v110 row_ror:2 row_mask:0xf bank_mask:0xf
	v_mov_b32_dpp v200, v111 row_ror:2 row_mask:0xf bank_mask:0xf
	v_pk_fma_f32 v[110:111], v[110:111], v[150:151], v[120:121]
	v_pk_mul_f32 v[120:121], v[140:141], v[186:187]
	v_pk_fma_f32 v[106:107], v[130:131], v[192:193], v[106:107]
	v_cndmask_b32_e64 v195, v224, v226, s[2:3]
	v_cndmask_b32_e64 v194, v220, v206, s[2:3]
; __device__ __forceinline__ unsigned cvt_pk_bf16(float lo, float hi) { f32x2_t f = {lo, hi}; bf16x2_t v = __builtin_convertvector(f, bf16x2_t); return __builtin_bit_cast(unsigned, v); }
; __device__ __forceinline__ float sigmoidf_(float x) { return __builtin_amdgcn_rcpf(1.0f + __expf(-x)); }
; #define SHI(lane, v, src) shfl_idx(lane, (v), (src))
;     __device__ __forceinline__ void operator()(const f32x4 (&acc)[2][2][4][2], const Unit& u, int wr, int wc, int fr, int fq) const {
;     ...
;             for (int q = 0; q < 8; ++q) {
;                 const int ai = q >> 2, m = q & 3;
;                 const f32x4 av = acc[ai][0][m][n], ag = acc[ai][1][m][n];
;                 f32x4 rv1, rv2, rg1, rg2;
; #pragma unroll
;                 for (int j = 0; j < 4; ++j) { rv1[j] = SHI(lane, av[j], src1); rv2[j] = SHI(lane, av[j], src2); rg1[j] = SHI(lane, ag[j], src1); rg2[j] = SHI(lane, ag[j], src2); }
;                 const f32x4 sv1 = fr >= 1 ? rv1 : pv1, sv2 = fr >= 2 ? rv2 : pv2, sg1 = fr >= 1 ? rg1 : pg1, sg2 = fr >= 2 ? rg2 : pg2;
;                 const f32x4 ov = wv[2] * av + wv[1] * sv1 + wv[0] * sv2;
;                 const f32x4 og = wg[2] * ag + wg[1] * sg1 + wg[0] * sg2;
;                 u32x2 w;
;                 w.x = cvt_pk_bf16(og[0] * sigmoidf_(og[0]) * ov[0], og[1] * sigmoidf_(og[1]) * ov[1]);
;                 w.y = cvt_pk_bf16(og[2] * sigmoidf_(og[2]) * ov[2], og[3] * sigmoidf_(og[3]) * ov[3]);
;                 *(u32x2*)(act + (size_t)(tok0 + q * 16) * DFF + ch) = w;
;                 if (q == 0 && fr < 2) { float* hp = halo + ((size_t)seg * 4 + fr) * NUP + ch; *(f32x4*)hp = av; *(f32x4*)(hp + DFF) = ag; }
;                 if (q == 7 && fr >= 14) { float* hp = halo + ((size_t)seg * 4 + (fr - 12)) * NUP + ch; *(f32x4*)hp = av; *(f32x4*)(hp + DFF) = ag; }
;                 pv1 = rv1; pv2 = rv2; pg1 = rg1; pg2 = rg2;
;             }
	v_pk_fma_f32 v[108:109], v[108:109], v[144:145], v[120:121]
	v_mul_f32_e32 v120, 0xbfb8aa3b, v106
	v_mul_f32_e32 v121, 0xbfb8aa3b, v107
	v_exp_f32_e32 v120, v120
	v_exp_f32_e32 v121, v121
	v_pk_fma_f32 v[108:109], v[132:133], v[194:195], v[108:109]
	v_cndmask_b32_e64 v127, v214, v200, s[2:3]
	v_mul_f32_e32 v124, 0xbfb8aa3b, v108
	v_mul_f32_e32 v125, 0xbfb8aa3b, v109
	v_exp_f32_e32 v124, v124
	v_exp_f32_e32 v125, v125
	v_add_f32_e32 v120, 1.0, v120
	v_add_f32_e32 v121, 1.0, v121
	v_rcp_f32_e32 v120, v120
	v_rcp_f32_e32 v121, v121
	v_add_f32_e32 v124, 1.0, v124
	v_add_f32_e32 v125, 1.0, v125
	v_rcp_f32_e32 v124, v124
	v_rcp_f32_e32 v125, v125
	v_cndmask_b32_e64 v126, v210, v196, s[2:3]
	v_pk_fma_f32 v[110:111], v[134:135], v[126:127], v[110:111]
	v_pk_mul_f32 v[106:107], v[106:107], v[120:121]
	v_cndmask_b32_e64 v129, v222, v208, s[2:3]
	v_cndmask_b32_e64 v128, v218, v204, s[2:3]
	v_pk_mul_f32 v[106:107], v[110:111], v[106:107]
	v_pk_fma_f32 v[112:113], v[136:137], v[128:129], v[112:113]
	v_cvt_pk_bf16_f32 v110, v106, v107
	v_pk_mul_f32 v[106:107], v[108:109], v[124:125]
	v_mov_b32_dpp v211, v104 row_ror:1 row_mask:0xf bank_mask:0xf
	v_mov_b32_dpp v215, v105 row_ror:1 row_mask:0xf bank_mask:0xf
	v_pk_mul_f32 v[106:107], v[112:113], v[106:107]
	v_mov_b32_dpp v192, v98 row_ror:1 row_mask:0xf bank_mask:0xf
	v_mov_b32_dpp v209, v99 row_ror:1 row_mask:0xf bank_mask:0xf
	v_cvt_pk_bf16_f32 v111, v106, v107
	v_or_b32_e32 v106, 32, v184
	v_mov_b32_dpp v186, v102 row_ror:1 row_mask:0xf bank_mask:0xf
	v_mov_b32_dpp v194, v103 row_ror:1 row_mask:0xf bank_mask:0xf
	v_mad_i64_i32 v[106:107], s[46:47], v106, s33, v[116:117]
	v_mov_b32_dpp v193, v98 row_ror:2 row_mask:0xf bank_mask:0xf
	v_mov_b32_dpp v210, v99 row_ror:2 row_mask:0xf bank_mask:0xf
	v_mov_b32_dpp v213, v100 row_ror:1 row_mask:0xf bank_mask:0xf
	v_mov_b32_dpp v217, v101 row_ror:1 row_mask:0xf bank_mask:0xf
	v_lshl_add_u64 v[106:107], v[106:107], 0, v[118:119]
	global_store_dwordx2 v[106:107], v[110:111], off
	v_mov_b32_dpp v214, v100 row_ror:2 row_mask:0xf bank_mask:0xf
	v_mov_b32_dpp v218, v101 row_ror:2 row_mask:0xf bank_mask:0xf
	v_cndmask_b32_e64 v111, v215, v207, s[0:1]
	v_cndmask_b32_e64 v110, v211, v203, s[0:1]
	v_cndmask_b32_e64 v125, v209, v201, s[0:1]
	v_cndmask_b32_e64 v124, v192, v197, s[0:1]
	v_pk_mul_f32 v[110:111], v[148:149], v[110:111]
	v_mov_b32_dpp v212, v104 row_ror:2 row_mask:0xf bank_mask:0xf
	v_mov_b32_dpp v216, v105 row_ror:2 row_mask:0xf bank_mask:0xf
	v_cndmask_b32_e64 v109, v194, v199, s[0:1]
	v_cndmask_b32_e64 v108, v186, v185, s[0:1]
	v_pk_fma_f32 v[104:105], v[104:105], v[152:153], v[110:111]
	v_pk_mul_f32 v[110:111], v[138:139], v[124:125]
	v_cndmask_b32_e64 v127, v217, v225, s[0:1]
	v_cndmask_b32_e64 v126, v213, v205, s[0:1]
	v_cndmask_b32_e64 v129, v202, v210, s[2:3]
	v_cndmask_b32_e64 v128, v198, v193, s[2:3]
	v_pk_mul_f32 v[108:109], v[146:147], v[108:109]
	v_pk_fma_f32 v[98:99], v[98:99], v[142:143], v[110:111]
	v_mov_b32_dpp v187, v102 row_ror:2 row_mask:0xf bank_mask:0xf
	v_mov_b32_dpp v195, v103 row_ror:2 row_mask:0xf bank_mask:0xf
	v_pk_fma_f32 v[102:103], v[102:103], v[150:151], v[108:109]
	v_pk_mul_f32 v[108:109], v[140:141], v[126:127]
	v_pk_fma_f32 v[98:99], v[130:131], v[128:129], v[98:99]
	v_cndmask_b32_e64 v179, v226, v218, s[2:3]
	v_cndmask_b32_e64 v178, v206, v214, s[2:3]
	v_pk_fma_f32 v[100:101], v[100:101], v[144:145], v[108:109]
	v_mul_f32_e32 v108, 0xbfb8aa3b, v98
	v_mul_f32_e32 v109, 0xbfb8aa3b, v99
	v_exp_f32_e32 v108, v108
	v_exp_f32_e32 v109, v109
	v_pk_fma_f32 v[100:101], v[132:133], v[178:179], v[100:101]
	v_cndmask_b32_e64 v113, v200, v195, s[2:3]
	v_mul_f32_e32 v110, 0xbfb8aa3b, v100
	v_mul_f32_e32 v111, 0xbfb8aa3b, v101
	v_exp_f32_e32 v110, v110
	v_exp_f32_e32 v111, v111
	v_add_f32_e32 v108, 1.0, v108
	v_add_f32_e32 v109, 1.0, v109
	v_rcp_f32_e32 v108, v108
	v_rcp_f32_e32 v109, v109
	v_add_f32_e32 v110, 1.0, v110
	v_add_f32_e32 v111, 1.0, v111
	v_rcp_f32_e32 v110, v110
	v_rcp_f32_e32 v111, v111
	v_cndmask_b32_e64 v112, v196, v187, s[2:3]
	v_pk_fma_f32 v[102:103], v[134:135], v[112:113], v[102:103]
	v_pk_mul_f32 v[98:99], v[98:99], v[108:109]
	v_cndmask_b32_e64 v121, v208, v216, s[2:3]
	v_cndmask_b32_e64 v120, v204, v212, s[2:3]
	v_pk_mul_f32 v[98:99], v[102:103], v[98:99]
	v_pk_fma_f32 v[104:105], v[136:137], v[120:121], v[104:105]
	v_cvt_pk_bf16_f32 v102, v98, v99
	v_pk_mul_f32 v[98:99], v[100:101], v[110:111]
	v_mov_b32_dpp v126, v94 row_ror:1 row_mask:0xf bank_mask:0xf
	v_mov_b32_dpp v178, v95 row_ror:1 row_mask:0xf bank_mask:0xf
	v_mov_b32_dpp v197, v96 row_ror:1 row_mask:0xf bank_mask:0xf
	v_mov_b32_dpp v201, v97 row_ror:1 row_mask:0xf bank_mask:0xf
	v_pk_mul_f32 v[98:99], v[104:105], v[98:99]
	v_mov_b32_dpp v128, v90 row_ror:1 row_mask:0xf bank_mask:0xf
	v_mov_b32_dpp v185, v91 row_ror:1 row_mask:0xf bank_mask:0xf
	v_mov_b32_dpp v199, v92 row_ror:1 row_mask:0xf bank_mask:0xf
	v_mov_b32_dpp v203, v93 row_ror:1 row_mask:0xf bank_mask:0xf
	v_cvt_pk_bf16_f32 v103, v98, v99
	v_or_b32_e32 v98, 48, v184
	v_mad_i64_i32 v[98:99], s[46:47], v98, s33, v[116:117]
	v_mov_b32_dpp v129, v90 row_ror:2 row_mask:0xf bank_mask:0xf
	v_mov_b32_dpp v196, v91 row_ror:2 row_mask:0xf bank_mask:0xf
	v_mov_b32_dpp v200, v92 row_ror:2 row_mask:0xf bank_mask:0xf
	v_mov_b32_dpp v204, v93 row_ror:2 row_mask:0xf bank_mask:0xf
	v_lshl_add_u64 v[98:99], v[98:99], 0, v[118:119]
	global_store_dwordx2 v[98:99], v[102:103], off
	v_cndmask_b32_e64 v101, v178, v194, s[0:1]
	v_cndmask_b32_e64 v100, v126, v186, s[0:1]
	v_cndmask_b32_e64 v103, v201, v215, s[0:1]
	v_cndmask_b32_e64 v102, v197, v211, s[0:1]
	v_cndmask_b32_e64 v111, v185, v209, s[0:1]
; __device__ __forceinline__ unsigned cvt_pk_bf16(float lo, float hi) { f32x2_t f = {lo, hi}; bf16x2_t v = __builtin_convertvector(f, bf16x2_t); return __builtin_bit_cast(unsigned, v); }
; __device__ __forceinline__ float sigmoidf_(float x) { return __builtin_amdgcn_rcpf(1.0f + __expf(-x)); }
; #define SHI(lane, v, src) shfl_idx(lane, (v), (src))
;     __device__ __forceinline__ void operator()(const f32x4 (&acc)[2][2][4][2], const Unit& u, int wr, int wc, int fr, int fq) const {
;     ...
;             for (int q = 0; q < 8; ++q) {
;                 const int ai = q >> 2, m = q & 3;
;                 const f32x4 av = acc[ai][0][m][n], ag = acc[ai][1][m][n];
;                 f32x4 rv1, rv2, rg1, rg2;
; #pragma unroll
;                 for (int j = 0; j < 4; ++j) { rv1[j] = SHI(lane, av[j], src1); rv2[j] = SHI(lane, av[j], src2); rg1[j] = SHI(lane, ag[j], src1); rg2[j] = SHI(lane, ag[j], src2); }
;                 const f32x4 sv1 = fr >= 1 ? rv1 : pv1, sv2 = fr >= 2 ? rv2 : pv2, sg1 = fr >= 1 ? rg1 : pg1, sg2 = fr >= 2 ? rg2 : pg2;
;                 const f32x4 ov = wv[2] * av + wv[1] * sv1 + wv[0] * sv2;
;                 const f32x4 og = wg[2] * ag + wg[1] * sg1 + wg[0] * sg2;
;                 u32x2 w;
;                 w.x = cvt_pk_bf16(og[0] * sigmoidf_(og[0]) * ov[0], og[1] * sigmoidf_(og[1]) * ov[1]);
;                 w.y = cvt_pk_bf16(og[2] * sigmoidf_(og[2]) * ov[2], og[3] * sigmoidf_(og[3]) * ov[3]);
;                 *(u32x2*)(act + (size_t)(tok0 + q * 16) * DFF + ch) = w;
;                 if (q == 0 && fr < 2) { float* hp = halo + ((size_t)seg * 4 + fr) * NUP + ch; *(f32x4*)hp = av; *(f32x4*)(hp + DFF) = ag; }
;                 if (q == 7 && fr >= 14) { float* hp = halo + ((size_t)seg * 4 + (fr - 12)) * NUP + ch; *(f32x4*)hp = av; *(f32x4*)(hp + DFF) = ag; }
;                 pv1 = rv1; pv2 = rv2; pg1 = rg1; pg2 = rg2;
;             }
	v_cndmask_b32_e64 v110, v128, v192, s[0:1]
	v_cndmask_b32_e64 v113, v203, v217, s[0:1]
	v_cndmask_b32_e64 v112, v199, v213, s[0:1]
	v_pk_mul_f32 v[102:103], v[148:149], v[102:103]
	v_pk_mul_f32 v[100:101], v[146:147], v[100:101]
	v_mov_b32_dpp v127, v94 row_ror:2 row_mask:0xf bank_mask:0xf
	v_mov_b32_dpp v179, v95 row_ror:2 row_mask:0xf bank_mask:0xf
	v_mov_b32_dpp v198, v96 row_ror:2 row_mask:0xf bank_mask:0xf
	v_mov_b32_dpp v202, v97 row_ror:2 row_mask:0xf bank_mask:0xf
	v_pk_fma_f32 v[94:95], v[94:95], v[150:151], v[100:101]
	v_pk_fma_f32 v[96:97], v[96:97], v[152:153], v[102:103]
	v_pk_mul_f32 v[100:101], v[140:141], v[112:113]
	v_pk_mul_f32 v[102:103], v[138:139], v[110:111]
	v_cndmask_b32_e64 v121, v210, v196, s[2:3]
	v_cndmask_b32_e64 v120, v193, v129, s[2:3]
	v_cndmask_b32_e64 v125, v218, v204, s[2:3]
	v_cndmask_b32_e64 v124, v214, v200, s[2:3]
	v_pk_fma_f32 v[90:91], v[90:91], v[142:143], v[102:103]
	v_pk_fma_f32 v[92:93], v[92:93], v[144:145], v[100:101]
	v_pk_fma_f32 v[90:91], v[130:131], v[120:121], v[90:91]
	v_pk_fma_f32 v[92:93], v[132:133], v[124:125], v[92:93]
	v_mul_f32_e32 v100, 0xbfb8aa3b, v90
	v_mul_f32_e32 v101, 0xbfb8aa3b, v91
	v_mul_f32_e32 v102, 0xbfb8aa3b, v92
	v_mul_f32_e32 v103, 0xbfb8aa3b, v93
	v_exp_f32_e32 v100, v100
	v_exp_f32_e32 v101, v101
	v_exp_f32_e32 v102, v102
	v_exp_f32_e32 v103, v103
	v_add_f32_e32 v100, 1.0, v100
	v_add_f32_e32 v101, 1.0, v101
	v_add_f32_e32 v102, 1.0, v102
	v_add_f32_e32 v103, 1.0, v103
	v_rcp_f32_e32 v100, v100
	v_rcp_f32_e32 v101, v101
	v_rcp_f32_e32 v102, v102
	v_rcp_f32_e32 v103, v103
	v_cndmask_b32_e64 v105, v195, v179, s[2:3]
	v_cndmask_b32_e64 v104, v187, v127, s[2:3]
	v_cndmask_b32_e64 v109, v216, v202, s[2:3]
	v_cndmask_b32_e64 v108, v212, v198, s[2:3]
	v_pk_fma_f32 v[96:97], v[136:137], v[108:109], v[96:97]
	v_pk_fma_f32 v[94:95], v[134:135], v[104:105], v[94:95]
	v_pk_mul_f32 v[90:91], v[90:91], v[100:101]
	v_pk_mul_f32 v[92:93], v[92:93], v[102:103]
	v_mov_b32_dpp v112, v86 row_ror:1 row_mask:0xf bank_mask:0xf
	v_mov_b32_dpp v124, v87 row_ror:1 row_mask:0xf bank_mask:0xf
	v_mov_b32_dpp v192, v88 row_ror:1 row_mask:0xf bank_mask:0xf
	v_mov_b32_dpp v205, v89 row_ror:1 row_mask:0xf bank_mask:0xf
	v_pk_mul_f32 v[90:91], v[94:95], v[90:91]
	v_pk_mul_f32 v[92:93], v[96:97], v[92:93]
	v_mov_b32_dpp v120, v82 row_ror:1 row_mask:0xf bank_mask:0xf
	v_mov_b32_dpp v186, v83 row_ror:1 row_mask:0xf bank_mask:0xf
	v_mov_b32_dpp v194, v84 row_ror:1 row_mask:0xf bank_mask:0xf
	v_mov_b32_dpp v207, v85 row_ror:1 row_mask:0xf bank_mask:0xf
	v_cvt_pk_bf16_f32 v90, v90, v91
	v_cvt_pk_bf16_f32 v91, v92, v93
	v_or_b32_e32 v92, 64, v184
	v_mad_i64_i32 v[92:93], s[46:47], v92, s33, v[116:117]
	v_mov_b32_dpp v121, v82 row_ror:2 row_mask:0xf bank_mask:0xf
	v_mov_b32_dpp v187, v83 row_ror:2 row_mask:0xf bank_mask:0xf
	v_mov_b32_dpp v195, v84 row_ror:2 row_mask:0xf bank_mask:0xf
	v_mov_b32_dpp v208, v85 row_ror:2 row_mask:0xf bank_mask:0xf
	v_lshl_add_u64 v[92:93], v[92:93], 0, v[118:119]
	global_store_dwordx2 v[92:93], v[90:91], off
	v_cndmask_b32_e64 v91, v124, v178, s[0:1]
	v_cndmask_b32_e64 v90, v112, v126, s[0:1]
	v_cndmask_b32_e64 v95, v205, v201, s[0:1]
	v_cndmask_b32_e64 v94, v192, v197, s[0:1]
	v_cndmask_b32_e64 v103, v186, v185, s[0:1]
	v_cndmask_b32_e64 v102, v120, v128, s[0:1]
	v_cndmask_b32_e64 v105, v207, v203, s[0:1]
	v_cndmask_b32_e64 v104, v194, v199, s[0:1]
	v_pk_mul_f32 v[94:95], v[148:149], v[94:95]
	v_pk_mul_f32 v[90:91], v[146:147], v[90:91]
	v_mov_b32_dpp v113, v86 row_ror:2 row_mask:0xf bank_mask:0xf
	v_mov_b32_dpp v125, v87 row_ror:2 row_mask:0xf bank_mask:0xf
	v_mov_b32_dpp v193, v88 row_ror:2 row_mask:0xf bank_mask:0xf
	v_mov_b32_dpp v206, v89 row_ror:2 row_mask:0xf bank_mask:0xf
	v_pk_fma_f32 v[86:87], v[86:87], v[150:151], v[90:91]
	v_pk_fma_f32 v[88:89], v[88:89], v[152:153], v[94:95]
	v_pk_mul_f32 v[90:91], v[140:141], v[104:105]
	v_pk_mul_f32 v[94:95], v[138:139], v[102:103]
	v_cndmask_b32_e64 v109, v196, v187, s[2:3]
	v_cndmask_b32_e64 v108, v129, v121, s[2:3]
	v_cndmask_b32_e64 v111, v204, v208, s[2:3]
	v_cndmask_b32_e64 v110, v200, v195, s[2:3]
	v_pk_fma_f32 v[82:83], v[82:83], v[142:143], v[94:95]
	v_pk_fma_f32 v[84:85], v[84:85], v[144:145], v[90:91]
	v_pk_fma_f32 v[82:83], v[130:131], v[108:109], v[82:83]
	v_pk_fma_f32 v[84:85], v[132:133], v[110:111], v[84:85]
	v_mul_f32_e32 v90, 0xbfb8aa3b, v82
	v_mul_f32_e32 v91, 0xbfb8aa3b, v83
	v_mul_f32_e32 v94, 0xbfb8aa3b, v84
	v_mul_f32_e32 v95, 0xbfb8aa3b, v85
	v_exp_f32_e32 v90, v90
	v_exp_f32_e32 v91, v91
	v_exp_f32_e32 v94, v94
	v_exp_f32_e32 v95, v95
	v_add_f32_e32 v90, 1.0, v90
	v_add_f32_e32 v91, 1.0, v91
	v_add_f32_e32 v94, 1.0, v94
	v_add_f32_e32 v95, 1.0, v95
	v_rcp_f32_e32 v90, v90
	v_rcp_f32_e32 v91, v91
	v_rcp_f32_e32 v94, v94
	v_rcp_f32_e32 v95, v95
	v_cndmask_b32_e64 v97, v179, v125, s[2:3]
	v_cndmask_b32_e64 v96, v127, v113, s[2:3]
	v_cndmask_b32_e64 v101, v202, v206, s[2:3]
	v_cndmask_b32_e64 v100, v198, v193, s[2:3]
	v_pk_fma_f32 v[88:89], v[136:137], v[100:101], v[88:89]
	v_pk_fma_f32 v[86:87], v[134:135], v[96:97], v[86:87]
	v_pk_mul_f32 v[82:83], v[82:83], v[90:91]
	v_pk_mul_f32 v[84:85], v[84:85], v[94:95]
	v_mov_b32_dpp v104, v78 row_ror:1 row_mask:0xf bank_mask:0xf
	v_mov_b32_dpp v110, v79 row_ror:1 row_mask:0xf bank_mask:0xf
	v_mov_b32_dpp v128, v80 row_ror:1 row_mask:0xf bank_mask:0xf
	v_mov_b32_dpp v185, v81 row_ror:1 row_mask:0xf bank_mask:0xf
	v_pk_mul_f32 v[82:83], v[86:87], v[82:83]
	v_pk_mul_f32 v[84:85], v[88:89], v[84:85]
	v_mov_b32_dpp v108, v74 row_ror:1 row_mask:0xf bank_mask:0xf
	v_mov_b32_dpp v126, v75 row_ror:1 row_mask:0xf bank_mask:0xf
	v_mov_b32_dpp v178, v76 row_ror:1 row_mask:0xf bank_mask:0xf
; __device__ __forceinline__ unsigned cvt_pk_bf16(float lo, float hi) { f32x2_t f = {lo, hi}; bf16x2_t v = __builtin_convertvector(f, bf16x2_t); return __builtin_bit_cast(unsigned, v); }
; __device__ __forceinline__ float sigmoidf_(float x) { return __builtin_amdgcn_rcpf(1.0f + __expf(-x)); }
; #define SHI(lane, v, src) shfl_idx(lane, (v), (src))
;     __device__ __forceinline__ void operator()(const f32x4 (&acc)[2][2][4][2], const Unit& u, int wr, int wc, int fr, int fq) const {
;     ...
;             for (int q = 0; q < 8; ++q) {
;                 const int ai = q >> 2, m = q & 3;
;                 const f32x4 av = acc[ai][0][m][n], ag = acc[ai][1][m][n];
;                 f32x4 rv1, rv2, rg1, rg2;
; #pragma unroll
;                 for (int j = 0; j < 4; ++j) { rv1[j] = SHI(lane, av[j], src1); rv2[j] = SHI(lane, av[j], src2); rg1[j] = SHI(lane, ag[j], src1); rg2[j] = SHI(lane, ag[j], src2); }
;                 const f32x4 sv1 = fr >= 1 ? rv1 : pv1, sv2 = fr >= 2 ? rv2 : pv2, sg1 = fr >= 1 ? rg1 : pg1, sg2 = fr >= 2 ? rg2 : pg2;
;                 const f32x4 ov = wv[2] * av + wv[1] * sv1 + wv[0] * sv2;
;                 const f32x4 og = wg[2] * ag + wg[1] * sg1 + wg[0] * sg2;
;                 u32x2 w;
;                 w.x = cvt_pk_bf16(og[0] * sigmoidf_(og[0]) * ov[0], og[1] * sigmoidf_(og[1]) * ov[1]);
;                 w.y = cvt_pk_bf16(og[2] * sigmoidf_(og[2]) * ov[2], og[3] * sigmoidf_(og[3]) * ov[3]);
;                 *(u32x2*)(act + (size_t)(tok0 + q * 16) * DFF + ch) = w;
;                 if (q == 0 && fr < 2) { float* hp = halo + ((size_t)seg * 4 + fr) * NUP + ch; *(f32x4*)hp = av; *(f32x4*)(hp + DFF) = ag; }
;                 if (q == 7 && fr >= 14) { float* hp = halo + ((size_t)seg * 4 + (fr - 12)) * NUP + ch; *(f32x4*)hp = av; *(f32x4*)(hp + DFF) = ag; }
	v_mov_b32_dpp v197, v77 row_ror:1 row_mask:0xf bank_mask:0xf
	v_cvt_pk_bf16_f32 v82, v82, v83
	v_cvt_pk_bf16_f32 v83, v84, v85
	v_or_b32_e32 v84, 0x50, v184
	v_mad_i64_i32 v[84:85], s[46:47], v84, s33, v[116:117]
	v_mov_b32_dpp v109, v74 row_ror:2 row_mask:0xf bank_mask:0xf
	v_mov_b32_dpp v127, v75 row_ror:2 row_mask:0xf bank_mask:0xf
	v_mov_b32_dpp v179, v76 row_ror:2 row_mask:0xf bank_mask:0xf
	v_mov_b32_dpp v198, v77 row_ror:2 row_mask:0xf bank_mask:0xf
	v_lshl_add_u64 v[94:95], v[84:85], 0, v[118:119]
	global_store_dwordx2 v[94:95], v[82:83], off
	v_cndmask_b32_e64 v83, v110, v124, s[0:1]
	v_cndmask_b32_e64 v82, v104, v112, s[0:1]
	v_cndmask_b32_e64 v85, v185, v205, s[0:1]
	v_cndmask_b32_e64 v84, v128, v192, s[0:1]
	v_cndmask_b32_e64 v91, v126, v186, s[0:1]
	v_cndmask_b32_e64 v90, v108, v120, s[0:1]
	v_cndmask_b32_e64 v97, v197, v207, s[0:1]
	v_cndmask_b32_e64 v96, v178, v194, s[0:1]
	v_pk_mul_f32 v[84:85], v[148:149], v[84:85]
	v_pk_mul_f32 v[82:83], v[146:147], v[82:83]
	v_mov_b32_dpp v105, v78 row_ror:2 row_mask:0xf bank_mask:0xf
	v_mov_b32_dpp v111, v79 row_ror:2 row_mask:0xf bank_mask:0xf
	v_mov_b32_dpp v129, v80 row_ror:2 row_mask:0xf bank_mask:0xf
	v_mov_b32_dpp v196, v81 row_ror:2 row_mask:0xf bank_mask:0xf
	v_pk_fma_f32 v[78:79], v[78:79], v[150:151], v[82:83]
	v_pk_fma_f32 v[80:81], v[80:81], v[152:153], v[84:85]
	v_pk_mul_f32 v[82:83], v[140:141], v[96:97]
	v_pk_mul_f32 v[84:85], v[138:139], v[90:91]
	v_cndmask_b32_e64 v101, v187, v127, s[2:3]
	v_cndmask_b32_e64 v100, v121, v109, s[2:3]
	v_cndmask_b32_e64 v103, v208, v198, s[2:3]
	v_cndmask_b32_e64 v102, v195, v179, s[2:3]
	v_pk_fma_f32 v[74:75], v[74:75], v[142:143], v[84:85]
	v_pk_fma_f32 v[76:77], v[76:77], v[144:145], v[82:83]
	v_pk_fma_f32 v[74:75], v[130:131], v[100:101], v[74:75]
	v_pk_fma_f32 v[76:77], v[132:133], v[102:103], v[76:77]
	v_mul_f32_e32 v82, 0xbfb8aa3b, v74
	v_mul_f32_e32 v83, 0xbfb8aa3b, v75
	v_mul_f32_e32 v84, 0xbfb8aa3b, v76
	v_mul_f32_e32 v85, 0xbfb8aa3b, v77
	v_exp_f32_e32 v82, v82
	v_exp_f32_e32 v83, v83
	v_exp_f32_e32 v84, v84
	v_exp_f32_e32 v85, v85
	v_add_f32_e32 v82, 1.0, v82
	v_add_f32_e32 v83, 1.0, v83
	v_add_f32_e32 v84, 1.0, v84
	v_add_f32_e32 v85, 1.0, v85
	v_rcp_f32_e32 v82, v82
	v_rcp_f32_e32 v83, v83
	v_rcp_f32_e32 v84, v84
	v_rcp_f32_e32 v85, v85
	v_cndmask_b32_e64 v87, v125, v111, s[2:3]
	v_cndmask_b32_e64 v86, v113, v105, s[2:3]
	v_cndmask_b32_e64 v89, v206, v196, s[2:3]
	v_cndmask_b32_e64 v88, v193, v129, s[2:3]
	v_pk_fma_f32 v[80:81], v[136:137], v[88:89], v[80:81]
	v_pk_fma_f32 v[78:79], v[134:135], v[86:87], v[78:79]
	v_pk_mul_f32 v[74:75], v[74:75], v[82:83]
	v_pk_mul_f32 v[76:77], v[76:77], v[84:85]
	v_pk_mul_f32 v[74:75], v[78:79], v[74:75]
	v_pk_mul_f32 v[76:77], v[80:81], v[76:77]
	v_cvt_pk_bf16_f32 v74, v74, v75
	v_cvt_pk_bf16_f32 v75, v76, v77
	v_or_b32_e32 v76, 0x60, v184
	v_mad_i64_i32 v[76:77], s[46:47], v76, s33, v[116:117]
	v_lshl_add_u64 v[96:97], v[76:77], 0, v[118:119]
	global_store_dwordx2 v[96:97], v[74:75], off
	v_mov_b32_dpp v74, v70 row_ror:1 row_mask:0xf bank_mask:0xf
	v_mov_b32_dpp v75, v71 row_ror:1 row_mask:0xf bank_mask:0xf
	v_mov_b32_dpp v76, v72 row_ror:1 row_mask:0xf bank_mask:0xf
	v_mov_b32_dpp v77, v73 row_ror:1 row_mask:0xf bank_mask:0xf
	v_mov_b32_dpp v78, v70 row_ror:2 row_mask:0xf bank_mask:0xf
	v_mov_b32_dpp v82, v66 row_ror:1 row_mask:0xf bank_mask:0xf
	v_mov_b32_dpp v79, v71 row_ror:2 row_mask:0xf bank_mask:0xf
	v_mov_b32_dpp v83, v67 row_ror:1 row_mask:0xf bank_mask:0xf
	v_mov_b32_dpp v80, v72 row_ror:2 row_mask:0xf bank_mask:0xf
	v_mov_b32_dpp v84, v68 row_ror:1 row_mask:0xf bank_mask:0xf
	v_mov_b32_dpp v81, v73 row_ror:2 row_mask:0xf bank_mask:0xf
	v_mov_b32_dpp v85, v69 row_ror:1 row_mask:0xf bank_mask:0xf
	v_mov_b32_dpp v86, v66 row_ror:2 row_mask:0xf bank_mask:0xf
	v_mov_b32_dpp v87, v67 row_ror:2 row_mask:0xf bank_mask:0xf
	v_mov_b32_dpp v88, v68 row_ror:2 row_mask:0xf bank_mask:0xf
	v_mov_b32_dpp v89, v69 row_ror:2 row_mask:0xf bank_mask:0xf
	v_cndmask_b32_e64 v75, v75, v110, s[0:1]
	v_cndmask_b32_e64 v74, v74, v104, s[0:1]
	v_cndmask_b32_e64 v77, v77, v185, s[0:1]
	v_cndmask_b32_e64 v76, v76, v128, s[0:1]
	v_pk_mul_f32 v[76:77], v[148:149], v[76:77]
	v_pk_mul_f32 v[74:75], v[146:147], v[74:75]
	v_cndmask_b32_e64 v79, v111, v79, s[2:3]
	v_cndmask_b32_e64 v78, v105, v78, s[2:3]
	v_cndmask_b32_e64 v81, v196, v81, s[2:3]
	v_cndmask_b32_e64 v80, v129, v80, s[2:3]
	v_cndmask_b32_e64 v83, v83, v126, s[0:1]
	v_cndmask_b32_e64 v82, v82, v108, s[0:1]
	v_cndmask_b32_e64 v85, v85, v197, s[0:1]
	v_cndmask_b32_e64 v84, v84, v178, s[0:1]
	v_pk_fma_f32 v[74:75], v[70:71], v[150:151], v[74:75]
	v_pk_fma_f32 v[76:77], v[72:73], v[152:153], v[76:77]
	v_pk_fma_f32 v[74:75], v[134:135], v[78:79], v[74:75]
	v_pk_fma_f32 v[76:77], v[136:137], v[80:81], v[76:77]
	v_pk_mul_f32 v[78:79], v[140:141], v[84:85]
	v_pk_mul_f32 v[80:81], v[138:139], v[82:83]
	v_cndmask_b32_e64 v87, v127, v87, s[2:3]
	v_cndmask_b32_e64 v86, v109, v86, s[2:3]
	v_cndmask_b32_e64 v89, v198, v89, s[2:3]
	v_cndmask_b32_e64 v88, v179, v88, s[2:3]
	v_pk_fma_f32 v[80:81], v[66:67], v[142:143], v[80:81]
	v_pk_fma_f32 v[78:79], v[68:69], v[144:145], v[78:79]
	v_pk_fma_f32 v[80:81], v[130:131], v[86:87], v[80:81]
	v_pk_fma_f32 v[78:79], v[132:133], v[88:89], v[78:79]
	v_mul_f32_e32 v82, 0xbfb8aa3b, v80
	v_mul_f32_e32 v83, 0xbfb8aa3b, v81
	v_mul_f32_e32 v84, 0xbfb8aa3b, v78
	v_mul_f32_e32 v85, 0xbfb8aa3b, v79
	v_exp_f32_e32 v82, v82
	v_exp_f32_e32 v83, v83
	v_exp_f32_e32 v84, v84
	v_exp_f32_e32 v85, v85
	v_add_f32_e32 v82, 1.0, v82
	v_add_f32_e32 v83, 1.0, v83
	v_add_f32_e32 v84, 1.0, v84
	v_add_f32_e32 v85, 1.0, v85
	v_rcp_f32_e32 v82, v82
	v_rcp_f32_e32 v83, v83
	v_rcp_f32_e32 v84, v84
	v_rcp_f32_e32 v85, v85
	v_pk_mul_f32 v[80:81], v[80:81], v[82:83]
	s_nop 0
	v_pk_mul_f32 v[74:75], v[74:75], v[80:81]
	v_pk_mul_f32 v[78:79], v[78:79], v[84:85]
	v_cvt_pk_bf16_f32 v74, v74, v75
	v_pk_mul_f32 v[76:77], v[76:77], v[78:79]
	s_nop 0
	v_cvt_pk_bf16_f32 v75, v76, v77
	v_or_b32_e32 v76, 0x70, v184
	v_mad_i64_i32 v[76:77], s[46:47], v76, s33, v[116:117]
	v_lshl_add_u64 v[100:101], v[76:77], 0, v[118:119]
	global_store_dwordx2 v[100:101], v[74:75], off
	v_lshl_add_u64 v[74:75], s[22:23], 0, v[122:123]
	v_lshl_add_u64 v[90:91], v[170:171], 2, v[74:75]
	s_and_saveexec_b64 s[76:77], s[6:7]
	s_cbranch_execz .LBB0_624
	global_store_dwordx4 v[90:91], v[70:73], off
	s_nop 1
	v_add_co_u32_e32 v70, vcc, 0x5000, v90
	s_nop 1
	v_addc_co_u32_e32 v71, vcc, 0, v91, vcc
	global_store_dwordx4 v[70:71], v[66:69], off offset:2048
; __device__ __forceinline__ unsigned cvt_pk_bf16(float lo, float hi) { f32x2_t f = {lo, hi}; bf16x2_t v = __builtin_convertvector(f, bf16x2_t); return __builtin_bit_cast(unsigned, v); }
; __device__ __forceinline__ float sigmoidf_(float x) { return __builtin_amdgcn_rcpf(1.0f + __expf(-x)); }
; #define SHI(lane, v, src) shfl_idx(lane, (v), (src))
;     __device__ __forceinline__ void operator()(const f32x4 (&acc)[2][2][4][2], const Unit& u, int wr, int wc, int fr, int fq) const {
;     ...
;         for (int n = 0; n < 2; ++n) {
;             const int ch = ch0 + 4 * n;
;             f32x4 wv[3], wg[3];
; #pragma unroll
;             for (int k = 0; k < 3; ++k) { wv[k] = *(const f32x4*)(cw + k * NUP + ch); wg[k] = *(const f32x4*)(cw + k * NUP + DFF + ch); }
;             f32x4 pv1 = {0.f, 0.f, 0.f, 0.f}, pv2 = pv1, pg1 = pv1, pg2 = pv1;
; #pragma unroll
;             for (int q = 0; q < 8; ++q) {
;                 const int ai = q >> 2, m = q & 3;
;                 const f32x4 av = acc[ai][0][m][n], ag = acc[ai][1][m][n];
;                 f32x4 rv1, rv2, rg1, rg2;
; #pragma unroll
;                 for (int j = 0; j < 4; ++j) { rv1[j] = SHI(lane, av[j], src1); rv2[j] = SHI(lane, av[j], src2); rg1[j] = SHI(lane, ag[j], src1); rg2[j] = SHI(lane, ag[j], src2); }
;                 const f32x4 sv1 = fr >= 1 ? rv1 : pv1, sv2 = fr >= 2 ? rv2 : pv2, sg1 = fr >= 1 ? rg1 : pg1, sg2 = fr >= 2 ? rg2 : pg2;
;                 const f32x4 ov = wv[2] * av + wv[1] * sv1 + wv[0] * sv2;
;                 const f32x4 og = wg[2] * ag + wg[1] * sg1 + wg[0] * sg2;
;                 u32x2 w;
;                 w.x = cvt_pk_bf16(og[0] * sigmoidf_(og[0]) * ov[0], og[1] * sigmoidf_(og[1]) * ov[1]);
;                 w.y = cvt_pk_bf16(og[2] * sigmoidf_(og[2]) * ov[2], og[3] * sigmoidf_(og[3]) * ov[3]);
;                 *(u32x2*)(act + (size_t)(tok0 + q * 16) * DFF + ch) = w;
;                 if (q == 0 && fr < 2) { float* hp = halo + ((size_t)seg * 4 + fr) * NUP + ch; *(f32x4*)hp = av; *(f32x4*)(hp + DFF) = ag; }
;                 if (q == 7 && fr >= 14) { float* hp = halo + ((size_t)seg * 4 + (fr - 12)) * NUP + ch; *(f32x4*)hp = av; *(f32x4*)(hp + DFF) = ag; }
;                 pv1 = rv1; pv2 = rv2; pg1 = rg1; pg2 = rg2;
;             }
.LBB0_624:
	s_or_b64 exec, exec, s[76:77]
	s_nop 0
	v_or_b32_e32 v66, 4, v170
	v_ashrrev_i32_e32 v67, 31, v66
	v_lshlrev_b64 v[66:67], 2, v[66:67]
	v_lshl_add_u64 v[68:69], s[26:27], 0, v[66:67]
	global_load_dwordx4 v[82:85], v[68:69], off
	v_lshl_add_u64 v[68:69], s[28:29], 0, v[66:67]
	global_load_dwordx4 v[70:73], v[68:69], off
	v_lshl_add_u64 v[68:69], s[30:31], 0, v[66:67]
	global_load_dwordx4 v[86:89], v[68:69], off
	v_lshl_add_u64 v[68:69], s[34:35], 0, v[66:67]
	global_load_dwordx4 v[74:77], v[68:69], off
	v_lshl_add_u64 v[66:67], s[24:25], 0, v[66:67]
	global_load_dwordx4 v[66:69], v[66:67], off
	s_nop 0
	global_load_dwordx4 v[78:81], v[172:173], off offset:16
	v_mov_b32_dpp v103, v58 row_ror:1 row_mask:0xf bank_mask:0xf
	v_mov_b32_dpp v108, v59 row_ror:1 row_mask:0xf bank_mask:0xf
	v_mov_b32_dpp v111, v60 row_ror:1 row_mask:0xf bank_mask:0xf
	v_mov_b32_dpp v119, v61 row_ror:1 row_mask:0xf bank_mask:0xf
	v_mov_b32_dpp v102, v58 row_ror:2 row_mask:0xf bank_mask:0xf
	v_mov_b32_dpp v104, v59 row_ror:2 row_mask:0xf bank_mask:0xf
	v_mov_b32_dpp v109, v60 row_ror:2 row_mask:0xf bank_mask:0xf
	v_mov_b32_dpp v116, v61 row_ror:2 row_mask:0xf bank_mask:0xf
	s_waitcnt lgkmcnt(0)
	v_cndmask_b32_e64 v131, v119, 0, s[0:1]
	v_cndmask_b32_e64 v130, v111, 0, s[0:1]
	v_cndmask_b32_e64 v133, v108, 0, s[0:1]
	v_cndmask_b32_e64 v132, v103, 0, s[0:1]
	v_cndmask_b32_e64 v135, 0, v104, s[2:3]
	v_cndmask_b32_e64 v134, 0, v102, s[2:3]
	v_cndmask_b32_e64 v137, 0, v116, s[2:3]
	v_cndmask_b32_e64 v136, 0, v109, s[2:3]
	v_mov_b32_dpp v110, v62 row_ror:1 row_mask:0xf bank_mask:0xf
	v_mov_b32_dpp v117, v63 row_ror:1 row_mask:0xf bank_mask:0xf
	v_mov_b32_dpp v118, v64 row_ror:1 row_mask:0xf bank_mask:0xf
	v_mov_b32_dpp v121, v65 row_ror:1 row_mask:0xf bank_mask:0xf
	v_mov_b32_dpp v105, v62 row_ror:2 row_mask:0xf bank_mask:0xf
	v_mov_b32_dpp v112, v63 row_ror:2 row_mask:0xf bank_mask:0xf
	v_mov_b32_dpp v113, v64 row_ror:2 row_mask:0xf bank_mask:0xf
	v_mov_b32_dpp v120, v65 row_ror:2 row_mask:0xf bank_mask:0xf
	v_cndmask_b32_e64 v123, v121, 0, s[0:1]
	v_cndmask_b32_e64 v122, v118, 0, s[0:1]
	v_cndmask_b32_e64 v125, v117, 0, s[0:1]
	v_cndmask_b32_e64 v124, v110, 0, s[0:1]
	v_cndmask_b32_e64 v127, 0, v112, s[2:3]
	v_cndmask_b32_e64 v126, 0, v105, s[2:3]
	v_cndmask_b32_e64 v129, 0, v120, s[2:3]
	v_cndmask_b32_e64 v128, 0, v113, s[2:3]
	s_waitcnt vmcnt(0)
	v_pk_mul_f32 v[124:125], v[82:83], v[124:125]
	v_pk_mul_f32 v[122:123], v[84:85], v[122:123]
	v_pk_mul_f32 v[132:133], v[70:71], v[132:133]
	v_pk_mul_f32 v[130:131], v[72:73], v[130:131]
	v_pk_fma_f32 v[122:123], v[64:65], v[88:89], v[122:123]
	v_pk_fma_f32 v[124:125], v[62:63], v[86:87], v[124:125]
	v_pk_fma_f32 v[130:131], v[60:61], v[76:77], v[130:131]
	v_pk_fma_f32 v[132:133], v[58:59], v[74:75], v[132:133]
	v_pk_fma_f32 v[130:131], v[68:69], v[136:137], v[130:131]
	v_pk_fma_f32 v[132:133], v[66:67], v[134:135], v[132:133]
	v_mul_f32_e32 v136, 0xbfb8aa3b, v130
	v_mul_f32_e32 v134, 0xbfb8aa3b, v132
	v_mul_f32_e32 v135, 0xbfb8aa3b, v133
	v_mul_f32_e32 v137, 0xbfb8aa3b, v131
	v_exp_f32_e32 v134, v134
	v_exp_f32_e32 v135, v135
	v_exp_f32_e32 v136, v136
	v_exp_f32_e32 v137, v137
	v_add_f32_e32 v134, 1.0, v134
	v_add_f32_e32 v135, 1.0, v135
	v_add_f32_e32 v136, 1.0, v136
	v_add_f32_e32 v137, 1.0, v137
	v_rcp_f32_e32 v134, v134
	v_rcp_f32_e32 v135, v135
	v_rcp_f32_e32 v136, v136
	v_rcp_f32_e32 v137, v137
	v_pk_fma_f32 v[122:123], v[80:81], v[128:129], v[122:123]
	v_pk_fma_f32 v[124:125], v[78:79], v[126:127], v[124:125]
	v_pk_mul_f32 v[126:127], v[132:133], v[134:135]
	v_pk_mul_f32 v[128:129], v[130:131], v[136:137]
	v_pk_mul_f32 v[124:125], v[124:125], v[126:127]
	v_pk_mul_f32 v[122:123], v[122:123], v[128:129]
	v_cvt_pk_bf16_f32 v124, v124, v125
	v_cvt_pk_bf16_f32 v125, v122, v123
	global_store_dwordx2 v[174:175], v[124:125], off offset:8
	s_and_saveexec_b64 s[76:77], s[4:5]
	v_readlane_b32 s58, v254, 16
	s_mov_b32 s39, 0xb2a5705f
	s_mov_b32 s38, 0x42ce8ed0
	s_cbranch_execz .LBB0_626
	global_store_dwordx4 v[176:177], v[62:65], off offset:16
	s_nop 1
	v_add_co_u32_e32 v62, vcc, 0x5000, v176
	s_nop 1
	v_addc_co_u32_e32 v63, vcc, 0, v177, vcc
	global_store_dwordx4 v[62:63], v[58:61], off offset:2064
.LBB0_626:
	s_or_b64 exec, exec, s[76:77]
	v_mov_b32_dpp v122, v54 row_ror:1 row_mask:0xf bank_mask:0xf
	v_mov_b32_dpp v126, v55 row_ror:1 row_mask:0xf bank_mask:0xf
	v_mov_b32_dpp v130, v56 row_ror:1 row_mask:0xf bank_mask:0xf
	v_mov_b32_dpp v134, v57 row_ror:1 row_mask:0xf bank_mask:0xf
	v_mov_b32_dpp v124, v50 row_ror:1 row_mask:0xf bank_mask:0xf
	v_mov_b32_dpp v127, v55 row_ror:2 row_mask:0xf bank_mask:0xf
	v_mov_b32_dpp v128, v51 row_ror:1 row_mask:0xf bank_mask:0xf
	v_mov_b32_dpp v131, v56 row_ror:2 row_mask:0xf bank_mask:0xf
	v_mov_b32_dpp v132, v52 row_ror:1 row_mask:0xf bank_mask:0xf
	v_mov_b32_dpp v136, v53 row_ror:1 row_mask:0xf bank_mask:0xf
	v_mov_b32_dpp v123, v54 row_ror:2 row_mask:0xf bank_mask:0xf
	v_mov_b32_dpp v125, v50 row_ror:2 row_mask:0xf bank_mask:0xf
	v_mov_b32_dpp v129, v51 row_ror:2 row_mask:0xf bank_mask:0xf
	v_mov_b32_dpp v133, v52 row_ror:2 row_mask:0xf bank_mask:0xf
	v_mov_b32_dpp v137, v53 row_ror:2 row_mask:0xf bank_mask:0xf
	s_waitcnt lgkmcnt(0)
; __device__ __forceinline__ unsigned cvt_pk_bf16(float lo, float hi) { f32x2_t f = {lo, hi}; bf16x2_t v = __builtin_convertvector(f, bf16x2_t); return __builtin_bit_cast(unsigned, v); }
; __device__ __forceinline__ float sigmoidf_(float x) { return __builtin_amdgcn_rcpf(1.0f + __expf(-x)); }
; #define SHI(lane, v, src) shfl_idx(lane, (v), (src))
;     __device__ __forceinline__ void operator()(const f32x4 (&acc)[2][2][4][2], const Unit& u, int wr, int wc, int fr, int fq) const {
;     ...
;             for (int q = 0; q < 8; ++q) {
;                 const int ai = q >> 2, m = q & 3;
;                 const f32x4 av = acc[ai][0][m][n], ag = acc[ai][1][m][n];
;                 f32x4 rv1, rv2, rg1, rg2;
; #pragma unroll
;                 for (int j = 0; j < 4; ++j) { rv1[j] = SHI(lane, av[j], src1); rv2[j] = SHI(lane, av[j], src2); rg1[j] = SHI(lane, ag[j], src1); rg2[j] = SHI(lane, ag[j], src2); }
;                 const f32x4 sv1 = fr >= 1 ? rv1 : pv1, sv2 = fr >= 2 ? rv2 : pv2, sg1 = fr >= 1 ? rg1 : pg1, sg2 = fr >= 2 ? rg2 : pg2;
;                 const f32x4 ov = wv[2] * av + wv[1] * sv1 + wv[0] * sv2;
;                 const f32x4 og = wg[2] * ag + wg[1] * sg1 + wg[0] * sg2;
;                 u32x2 w;
;                 w.x = cvt_pk_bf16(og[0] * sigmoidf_(og[0]) * ov[0], og[1] * sigmoidf_(og[1]) * ov[1]);
;                 w.y = cvt_pk_bf16(og[2] * sigmoidf_(og[2]) * ov[2], og[3] * sigmoidf_(og[3]) * ov[3]);
;                 *(u32x2*)(act + (size_t)(tok0 + q * 16) * DFF + ch) = w;
;                 if (q == 0 && fr < 2) { float* hp = halo + ((size_t)seg * 4 + fr) * NUP + ch; *(f32x4*)hp = av; *(f32x4*)(hp + DFF) = ag; }
;                 if (q == 7 && fr >= 14) { float* hp = halo + ((size_t)seg * 4 + (fr - 12)) * NUP + ch; *(f32x4*)hp = av; *(f32x4*)(hp + DFF) = ag; }
;                 pv1 = rv1; pv2 = rv2; pg1 = rg1; pg2 = rg2;
;             }
	v_cndmask_b32_e64 v59, v126, v117, s[0:1]
	v_cndmask_b32_e64 v58, v122, v110, s[0:1]
	v_cndmask_b32_e64 v61, v134, v121, s[0:1]
	v_cndmask_b32_e64 v60, v130, v118, s[0:1]
	v_cndmask_b32_e64 v63, v112, v127, s[2:3]
	v_cndmask_b32_e64 v64, v113, v131, s[2:3]
	v_cndmask_b32_e64 v113, v128, v108, s[0:1]
	v_cndmask_b32_e64 v112, v124, v103, s[0:1]
	v_cndmask_b32_e64 v119, v136, v119, s[0:1]
	v_cndmask_b32_e64 v118, v132, v111, s[0:1]
	v_pk_mul_f32 v[60:61], v[84:85], v[60:61]
	v_pk_mul_f32 v[58:59], v[82:83], v[58:59]
	v_mov_b32_dpp v135, v57 row_ror:2 row_mask:0xf bank_mask:0xf
	v_pk_fma_f32 v[54:55], v[54:55], v[86:87], v[58:59]
	v_pk_fma_f32 v[56:57], v[56:57], v[88:89], v[60:61]
	v_pk_mul_f32 v[58:59], v[72:73], v[118:119]
	v_pk_mul_f32 v[60:61], v[70:71], v[112:113]
	v_cndmask_b32_e64 v62, v105, v123, s[2:3]
	v_cndmask_b32_e64 v103, v104, v129, s[2:3]
	v_cndmask_b32_e64 v102, v102, v125, s[2:3]
	v_cndmask_b32_e64 v105, v116, v137, s[2:3]
	v_cndmask_b32_e64 v104, v109, v133, s[2:3]
	v_pk_fma_f32 v[50:51], v[50:51], v[74:75], v[60:61]
	v_pk_fma_f32 v[52:53], v[52:53], v[76:77], v[58:59]
	v_pk_fma_f32 v[50:51], v[66:67], v[102:103], v[50:51]
	v_pk_fma_f32 v[52:53], v[68:69], v[104:105], v[52:53]
	v_mul_f32_e32 v58, 0xbfb8aa3b, v50
	v_mul_f32_e32 v59, 0xbfb8aa3b, v51
	v_mul_f32_e32 v60, 0xbfb8aa3b, v52
	v_mul_f32_e32 v61, 0xbfb8aa3b, v53
	v_exp_f32_e32 v58, v58
	v_exp_f32_e32 v59, v59
	v_exp_f32_e32 v60, v60
	v_exp_f32_e32 v61, v61
	v_add_f32_e32 v58, 1.0, v58
	v_add_f32_e32 v59, 1.0, v59
	v_add_f32_e32 v60, 1.0, v60
	v_add_f32_e32 v61, 1.0, v61
	v_rcp_f32_e32 v58, v58
	v_rcp_f32_e32 v59, v59
	v_rcp_f32_e32 v60, v60
	v_rcp_f32_e32 v61, v61
	v_cndmask_b32_e64 v65, v120, v135, s[2:3]
	v_pk_fma_f32 v[56:57], v[80:81], v[64:65], v[56:57]
	v_pk_fma_f32 v[54:55], v[78:79], v[62:63], v[54:55]
	v_pk_mul_f32 v[50:51], v[50:51], v[58:59]
	v_pk_mul_f32 v[52:53], v[52:53], v[60:61]
	v_pk_mul_f32 v[50:51], v[54:55], v[50:51]
	v_pk_mul_f32 v[52:53], v[56:57], v[52:53]
	v_cvt_pk_bf16_f32 v50, v50, v51
	v_cvt_pk_bf16_f32 v51, v52, v53
	v_mov_b32_dpp v102, v46 row_ror:1 row_mask:0xf bank_mask:0xf
	v_mov_b32_dpp v108, v47 row_ror:1 row_mask:0xf bank_mask:0xf
	v_mov_b32_dpp v112, v48 row_ror:1 row_mask:0xf bank_mask:0xf
	v_mov_b32_dpp v116, v49 row_ror:1 row_mask:0xf bank_mask:0xf
	global_store_dwordx2 v[114:115], v[50:51], off offset:8
	v_mov_b32_dpp v104, v42 row_ror:1 row_mask:0xf bank_mask:0xf
	v_mov_b32_dpp v110, v43 row_ror:1 row_mask:0xf bank_mask:0xf
	v_mov_b32_dpp v114, v44 row_ror:1 row_mask:0xf bank_mask:0xf
	v_mov_b32_dpp v118, v45 row_ror:1 row_mask:0xf bank_mask:0xf
	v_mov_b32_dpp v105, v42 row_ror:2 row_mask:0xf bank_mask:0xf
	v_mov_b32_dpp v111, v43 row_ror:2 row_mask:0xf bank_mask:0xf
	v_mov_b32_dpp v115, v44 row_ror:2 row_mask:0xf bank_mask:0xf
	v_mov_b32_dpp v119, v45 row_ror:2 row_mask:0xf bank_mask:0xf
	v_cndmask_b32_e64 v51, v108, v126, s[0:1]
	v_cndmask_b32_e64 v50, v102, v122, s[0:1]
	v_cndmask_b32_e64 v53, v116, v134, s[0:1]
	v_cndmask_b32_e64 v52, v112, v130, s[0:1]
	v_cndmask_b32_e64 v59, v110, v128, s[0:1]
	v_cndmask_b32_e64 v58, v104, v124, s[0:1]
	v_cndmask_b32_e64 v61, v118, v136, s[0:1]
	v_cndmask_b32_e64 v60, v114, v132, s[0:1]
	v_pk_mul_f32 v[52:53], v[84:85], v[52:53]
	v_pk_mul_f32 v[50:51], v[82:83], v[50:51]
	v_mov_b32_dpp v103, v46 row_ror:2 row_mask:0xf bank_mask:0xf
	v_mov_b32_dpp v109, v47 row_ror:2 row_mask:0xf bank_mask:0xf
	v_mov_b32_dpp v113, v48 row_ror:2 row_mask:0xf bank_mask:0xf
	v_mov_b32_dpp v117, v49 row_ror:2 row_mask:0xf bank_mask:0xf
	v_pk_fma_f32 v[46:47], v[46:47], v[86:87], v[50:51]
	v_pk_fma_f32 v[48:49], v[48:49], v[88:89], v[52:53]
	v_pk_mul_f32 v[50:51], v[72:73], v[60:61]
	v_pk_mul_f32 v[52:53], v[70:71], v[58:59]
	v_cndmask_b32_e64 v63, v129, v111, s[2:3]
	v_cndmask_b32_e64 v62, v125, v105, s[2:3]
	v_cndmask_b32_e64 v65, v137, v119, s[2:3]
	v_cndmask_b32_e64 v64, v133, v115, s[2:3]
	v_pk_fma_f32 v[42:43], v[42:43], v[74:75], v[52:53]
	v_pk_fma_f32 v[44:45], v[44:45], v[76:77], v[50:51]
	v_pk_fma_f32 v[42:43], v[66:67], v[62:63], v[42:43]
	v_pk_fma_f32 v[44:45], v[68:69], v[64:65], v[44:45]
	v_mul_f32_e32 v50, 0xbfb8aa3b, v42
	v_mul_f32_e32 v51, 0xbfb8aa3b, v43
	v_mul_f32_e32 v52, 0xbfb8aa3b, v44
	v_mul_f32_e32 v53, 0xbfb8aa3b, v45
	v_exp_f32_e32 v50, v50
	v_exp_f32_e32 v51, v51
	v_exp_f32_e32 v52, v52
	v_exp_f32_e32 v53, v53
	v_add_f32_e32 v50, 1.0, v50
	v_add_f32_e32 v51, 1.0, v51
	v_add_f32_e32 v52, 1.0, v52
	v_add_f32_e32 v53, 1.0, v53
	v_rcp_f32_e32 v50, v50
	v_rcp_f32_e32 v51, v51
	v_rcp_f32_e32 v52, v52
	v_rcp_f32_e32 v53, v53
	v_cndmask_b32_e64 v55, v127, v109, s[2:3]
	v_cndmask_b32_e64 v54, v123, v103, s[2:3]
	v_cndmask_b32_e64 v57, v135, v117, s[2:3]
	v_cndmask_b32_e64 v56, v131, v113, s[2:3]
	v_pk_fma_f32 v[48:49], v[80:81], v[56:57], v[48:49]
	v_pk_fma_f32 v[46:47], v[78:79], v[54:55], v[46:47]
	v_pk_mul_f32 v[42:43], v[42:43], v[50:51]
	v_pk_mul_f32 v[44:45], v[44:45], v[52:53]
	v_pk_mul_f32 v[42:43], v[46:47], v[42:43]
	v_pk_mul_f32 v[44:45], v[48:49], v[44:45]
	v_cvt_pk_bf16_f32 v42, v42, v43
	v_cvt_pk_bf16_f32 v43, v44, v45
	global_store_dwordx2 v[106:107], v[42:43], off offset:8
	v_mov_b32_dpp v58, v38 row_ror:1 row_mask:0xf bank_mask:0xf
	v_mov_b32_dpp v62, v39 row_ror:1 row_mask:0xf bank_mask:0xf
	v_mov_b32_dpp v106, v40 row_ror:1 row_mask:0xf bank_mask:0xf
	v_mov_b32_dpp v122, v41 row_ror:1 row_mask:0xf bank_mask:0xf
	v_mov_b32_dpp v60, v34 row_ror:1 row_mask:0xf bank_mask:0xf
	v_mov_b32_dpp v64, v35 row_ror:1 row_mask:0xf bank_mask:0xf
	v_mov_b32_dpp v120, v36 row_ror:1 row_mask:0xf bank_mask:0xf
	v_mov_b32_dpp v124, v37 row_ror:1 row_mask:0xf bank_mask:0xf
; __device__ __forceinline__ unsigned cvt_pk_bf16(float lo, float hi) { f32x2_t f = {lo, hi}; bf16x2_t v = __builtin_convertvector(f, bf16x2_t); return __builtin_bit_cast(unsigned, v); }
; __device__ __forceinline__ float sigmoidf_(float x) { return __builtin_amdgcn_rcpf(1.0f + __expf(-x)); }
; #define SHI(lane, v, src) shfl_idx(lane, (v), (src))
;     __device__ __forceinline__ void operator()(const f32x4 (&acc)[2][2][4][2], const Unit& u, int wr, int wc, int fr, int fq) const {
;     ...
;             for (int q = 0; q < 8; ++q) {
;                 const int ai = q >> 2, m = q & 3;
;                 const f32x4 av = acc[ai][0][m][n], ag = acc[ai][1][m][n];
;                 f32x4 rv1, rv2, rg1, rg2;
; #pragma unroll
;                 for (int j = 0; j < 4; ++j) { rv1[j] = SHI(lane, av[j], src1); rv2[j] = SHI(lane, av[j], src2); rg1[j] = SHI(lane, ag[j], src1); rg2[j] = SHI(lane, ag[j], src2); }
;                 const f32x4 sv1 = fr >= 1 ? rv1 : pv1, sv2 = fr >= 2 ? rv2 : pv2, sg1 = fr >= 1 ? rg1 : pg1, sg2 = fr >= 2 ? rg2 : pg2;
;                 const f32x4 ov = wv[2] * av + wv[1] * sv1 + wv[0] * sv2;
;                 const f32x4 og = wg[2] * ag + wg[1] * sg1 + wg[0] * sg2;
;                 u32x2 w;
;                 w.x = cvt_pk_bf16(og[0] * sigmoidf_(og[0]) * ov[0], og[1] * sigmoidf_(og[1]) * ov[1]);
;                 w.y = cvt_pk_bf16(og[2] * sigmoidf_(og[2]) * ov[2], og[3] * sigmoidf_(og[3]) * ov[3]);
;                 *(u32x2*)(act + (size_t)(tok0 + q * 16) * DFF + ch) = w;
;                 if (q == 0 && fr < 2) { float* hp = halo + ((size_t)seg * 4 + fr) * NUP + ch; *(f32x4*)hp = av; *(f32x4*)(hp + DFF) = ag; }
;                 if (q == 7 && fr >= 14) { float* hp = halo + ((size_t)seg * 4 + (fr - 12)) * NUP + ch; *(f32x4*)hp = av; *(f32x4*)(hp + DFF) = ag; }
;                 pv1 = rv1; pv2 = rv2; pg1 = rg1; pg2 = rg2;
;             }
	v_mov_b32_dpp v61, v34 row_ror:2 row_mask:0xf bank_mask:0xf
	v_mov_b32_dpp v65, v35 row_ror:2 row_mask:0xf bank_mask:0xf
	v_mov_b32_dpp v121, v36 row_ror:2 row_mask:0xf bank_mask:0xf
	v_mov_b32_dpp v125, v37 row_ror:2 row_mask:0xf bank_mask:0xf
	v_cndmask_b32_e64 v43, v62, v108, s[0:1]
	v_cndmask_b32_e64 v42, v58, v102, s[0:1]
	v_cndmask_b32_e64 v45, v122, v116, s[0:1]
	v_cndmask_b32_e64 v44, v106, v112, s[0:1]
	v_cndmask_b32_e64 v51, v64, v110, s[0:1]
	v_cndmask_b32_e64 v50, v60, v104, s[0:1]
	v_cndmask_b32_e64 v53, v124, v118, s[0:1]
	v_cndmask_b32_e64 v52, v120, v114, s[0:1]
	v_pk_mul_f32 v[44:45], v[84:85], v[44:45]
	v_pk_mul_f32 v[42:43], v[82:83], v[42:43]
	v_mov_b32_dpp v59, v38 row_ror:2 row_mask:0xf bank_mask:0xf
	v_mov_b32_dpp v63, v39 row_ror:2 row_mask:0xf bank_mask:0xf
	v_mov_b32_dpp v107, v40 row_ror:2 row_mask:0xf bank_mask:0xf
	v_mov_b32_dpp v123, v41 row_ror:2 row_mask:0xf bank_mask:0xf
	v_pk_fma_f32 v[38:39], v[38:39], v[86:87], v[42:43]
	v_pk_fma_f32 v[40:41], v[40:41], v[88:89], v[44:45]
	v_pk_mul_f32 v[42:43], v[72:73], v[52:53]
	v_pk_mul_f32 v[44:45], v[70:71], v[50:51]
	v_cndmask_b32_e64 v55, v111, v65, s[2:3]
	v_cndmask_b32_e64 v54, v105, v61, s[2:3]
	v_cndmask_b32_e64 v57, v119, v125, s[2:3]
	v_cndmask_b32_e64 v56, v115, v121, s[2:3]
	v_pk_fma_f32 v[34:35], v[34:35], v[74:75], v[44:45]
	v_pk_fma_f32 v[36:37], v[36:37], v[76:77], v[42:43]
	v_pk_fma_f32 v[34:35], v[66:67], v[54:55], v[34:35]
	v_pk_fma_f32 v[36:37], v[68:69], v[56:57], v[36:37]
	v_mul_f32_e32 v42, 0xbfb8aa3b, v34
	v_mul_f32_e32 v43, 0xbfb8aa3b, v35
	v_mul_f32_e32 v44, 0xbfb8aa3b, v36
	v_mul_f32_e32 v45, 0xbfb8aa3b, v37
	v_exp_f32_e32 v42, v42
	v_exp_f32_e32 v43, v43
	v_exp_f32_e32 v44, v44
	v_exp_f32_e32 v45, v45
	v_add_f32_e32 v42, 1.0, v42
	v_add_f32_e32 v43, 1.0, v43
	v_add_f32_e32 v44, 1.0, v44
	v_add_f32_e32 v45, 1.0, v45
	v_rcp_f32_e32 v42, v42
	v_rcp_f32_e32 v43, v43
	v_rcp_f32_e32 v44, v44
	v_rcp_f32_e32 v45, v45
	v_cndmask_b32_e64 v47, v109, v63, s[2:3]
	v_cndmask_b32_e64 v46, v103, v59, s[2:3]
	v_cndmask_b32_e64 v49, v117, v123, s[2:3]
	v_cndmask_b32_e64 v48, v113, v107, s[2:3]
	v_pk_fma_f32 v[40:41], v[80:81], v[48:49], v[40:41]
	v_pk_fma_f32 v[38:39], v[78:79], v[46:47], v[38:39]
	v_pk_mul_f32 v[34:35], v[34:35], v[42:43]
	v_pk_mul_f32 v[36:37], v[36:37], v[44:45]
	v_pk_mul_f32 v[34:35], v[38:39], v[34:35]
	v_pk_mul_f32 v[36:37], v[40:41], v[36:37]
	v_cvt_pk_bf16_f32 v34, v34, v35
	v_cvt_pk_bf16_f32 v35, v36, v37
	global_store_dwordx2 v[98:99], v[34:35], off offset:8
	v_mov_b32_dpp v50, v30 row_ror:1 row_mask:0xf bank_mask:0xf
	v_mov_b32_dpp v54, v31 row_ror:1 row_mask:0xf bank_mask:0xf
	v_mov_b32_dpp v98, v32 row_ror:1 row_mask:0xf bank_mask:0xf
	v_mov_b32_dpp v104, v33 row_ror:1 row_mask:0xf bank_mask:0xf
	v_mov_b32_dpp v52, v26 row_ror:1 row_mask:0xf bank_mask:0xf
	v_mov_b32_dpp v56, v27 row_ror:1 row_mask:0xf bank_mask:0xf
	v_mov_b32_dpp v102, v28 row_ror:1 row_mask:0xf bank_mask:0xf
	v_mov_b32_dpp v108, v29 row_ror:1 row_mask:0xf bank_mask:0xf
	v_mov_b32_dpp v53, v26 row_ror:2 row_mask:0xf bank_mask:0xf
	v_mov_b32_dpp v57, v27 row_ror:2 row_mask:0xf bank_mask:0xf
	v_mov_b32_dpp v103, v28 row_ror:2 row_mask:0xf bank_mask:0xf
	v_mov_b32_dpp v109, v29 row_ror:2 row_mask:0xf bank_mask:0xf
	v_cndmask_b32_e64 v35, v54, v62, s[0:1]
	v_cndmask_b32_e64 v34, v50, v58, s[0:1]
	v_cndmask_b32_e64 v37, v104, v122, s[0:1]
	v_cndmask_b32_e64 v36, v98, v106, s[0:1]
	v_cndmask_b32_e64 v43, v56, v64, s[0:1]
	v_cndmask_b32_e64 v42, v52, v60, s[0:1]
	v_cndmask_b32_e64 v45, v108, v124, s[0:1]
	v_cndmask_b32_e64 v44, v102, v120, s[0:1]
	v_pk_mul_f32 v[36:37], v[84:85], v[36:37]
	v_pk_mul_f32 v[34:35], v[82:83], v[34:35]
	v_mov_b32_dpp v51, v30 row_ror:2 row_mask:0xf bank_mask:0xf
	v_mov_b32_dpp v55, v31 row_ror:2 row_mask:0xf bank_mask:0xf
	v_mov_b32_dpp v99, v32 row_ror:2 row_mask:0xf bank_mask:0xf
	v_mov_b32_dpp v105, v33 row_ror:2 row_mask:0xf bank_mask:0xf
	v_pk_fma_f32 v[30:31], v[30:31], v[86:87], v[34:35]
	v_pk_fma_f32 v[32:33], v[32:33], v[88:89], v[36:37]
	v_pk_mul_f32 v[34:35], v[72:73], v[44:45]
	v_pk_mul_f32 v[36:37], v[70:71], v[42:43]
	v_cndmask_b32_e64 v47, v65, v57, s[2:3]
	v_cndmask_b32_e64 v46, v61, v53, s[2:3]
	v_cndmask_b32_e64 v49, v125, v109, s[2:3]
	v_cndmask_b32_e64 v48, v121, v103, s[2:3]
	v_pk_fma_f32 v[26:27], v[26:27], v[74:75], v[36:37]
	v_pk_fma_f32 v[28:29], v[28:29], v[76:77], v[34:35]
	v_pk_fma_f32 v[26:27], v[66:67], v[46:47], v[26:27]
	v_pk_fma_f32 v[28:29], v[68:69], v[48:49], v[28:29]
	v_mul_f32_e32 v34, 0xbfb8aa3b, v26
	v_mul_f32_e32 v35, 0xbfb8aa3b, v27
	v_mul_f32_e32 v36, 0xbfb8aa3b, v28
	v_mul_f32_e32 v37, 0xbfb8aa3b, v29
	v_exp_f32_e32 v34, v34
	v_exp_f32_e32 v35, v35
	v_exp_f32_e32 v36, v36
	v_exp_f32_e32 v37, v37
	v_add_f32_e32 v34, 1.0, v34
	v_add_f32_e32 v35, 1.0, v35
	v_add_f32_e32 v36, 1.0, v36
	v_add_f32_e32 v37, 1.0, v37
	v_rcp_f32_e32 v34, v34
	v_rcp_f32_e32 v35, v35
	v_rcp_f32_e32 v36, v36
	v_rcp_f32_e32 v37, v37
	v_mov_b32_dpp v42, v22 row_ror:1 row_mask:0xf bank_mask:0xf
	v_mov_b32_dpp v46, v23 row_ror:1 row_mask:0xf bank_mask:0xf
	v_mov_b32_dpp v58, v24 row_ror:1 row_mask:0xf bank_mask:0xf
	v_mov_b32_dpp v62, v25 row_ror:1 row_mask:0xf bank_mask:0xf
	v_cndmask_b32_e64 v39, v63, v55, s[2:3]
	v_cndmask_b32_e64 v38, v59, v51, s[2:3]
	v_cndmask_b32_e64 v41, v123, v105, s[2:3]
	v_cndmask_b32_e64 v40, v107, v99, s[2:3]
	v_mov_b32_dpp v44, v18 row_ror:1 row_mask:0xf bank_mask:0xf
	v_mov_b32_dpp v48, v19 row_ror:1 row_mask:0xf bank_mask:0xf
	v_mov_b32_dpp v60, v20 row_ror:1 row_mask:0xf bank_mask:0xf
	v_mov_b32_dpp v64, v21 row_ror:1 row_mask:0xf bank_mask:0xf
	v_pk_fma_f32 v[32:33], v[80:81], v[40:41], v[32:33]
; __device__ __forceinline__ unsigned cvt_pk_bf16(float lo, float hi) { f32x2_t f = {lo, hi}; bf16x2_t v = __builtin_convertvector(f, bf16x2_t); return __builtin_bit_cast(unsigned, v); }
; __device__ __forceinline__ float sigmoidf_(float x) { return __builtin_amdgcn_rcpf(1.0f + __expf(-x)); }
; #define SHI(lane, v, src) shfl_idx(lane, (v), (src))
;     __device__ __forceinline__ void operator()(const f32x4 (&acc)[2][2][4][2], const Unit& u, int wr, int wc, int fr, int fq) const {
;     ...
;             for (int q = 0; q < 8; ++q) {
;                 const int ai = q >> 2, m = q & 3;
;                 const f32x4 av = acc[ai][0][m][n], ag = acc[ai][1][m][n];
;                 f32x4 rv1, rv2, rg1, rg2;
; #pragma unroll
;                 for (int j = 0; j < 4; ++j) { rv1[j] = SHI(lane, av[j], src1); rv2[j] = SHI(lane, av[j], src2); rg1[j] = SHI(lane, ag[j], src1); rg2[j] = SHI(lane, ag[j], src2); }
;                 const f32x4 sv1 = fr >= 1 ? rv1 : pv1, sv2 = fr >= 2 ? rv2 : pv2, sg1 = fr >= 1 ? rg1 : pg1, sg2 = fr >= 2 ? rg2 : pg2;
;                 const f32x4 ov = wv[2] * av + wv[1] * sv1 + wv[0] * sv2;
;                 const f32x4 og = wg[2] * ag + wg[1] * sg1 + wg[0] * sg2;
;                 u32x2 w;
;                 w.x = cvt_pk_bf16(og[0] * sigmoidf_(og[0]) * ov[0], og[1] * sigmoidf_(og[1]) * ov[1]);
;                 w.y = cvt_pk_bf16(og[2] * sigmoidf_(og[2]) * ov[2], og[3] * sigmoidf_(og[3]) * ov[3]);
;                 *(u32x2*)(act + (size_t)(tok0 + q * 16) * DFF + ch) = w;
;                 if (q == 0 && fr < 2) { float* hp = halo + ((size_t)seg * 4 + fr) * NUP + ch; *(f32x4*)hp = av; *(f32x4*)(hp + DFF) = ag; }
;                 if (q == 7 && fr >= 14) { float* hp = halo + ((size_t)seg * 4 + (fr - 12)) * NUP + ch; *(f32x4*)hp = av; *(f32x4*)(hp + DFF) = ag; }
;                 pv1 = rv1; pv2 = rv2; pg1 = rg1; pg2 = rg2;
;             }
	v_pk_fma_f32 v[30:31], v[78:79], v[38:39], v[30:31]
	v_pk_mul_f32 v[26:27], v[26:27], v[34:35]
	v_pk_mul_f32 v[28:29], v[28:29], v[36:37]
	v_pk_mul_f32 v[26:27], v[30:31], v[26:27]
	v_pk_mul_f32 v[28:29], v[32:33], v[28:29]
	v_mov_b32_dpp v45, v18 row_ror:2 row_mask:0xf bank_mask:0xf
	v_mov_b32_dpp v49, v19 row_ror:2 row_mask:0xf bank_mask:0xf
	v_mov_b32_dpp v61, v20 row_ror:2 row_mask:0xf bank_mask:0xf
	v_mov_b32_dpp v65, v21 row_ror:2 row_mask:0xf bank_mask:0xf
	v_cvt_pk_bf16_f32 v26, v26, v27
	v_cvt_pk_bf16_f32 v27, v28, v29
	global_store_dwordx2 v[92:93], v[26:27], off offset:8
	v_cndmask_b32_e64 v27, v46, v54, s[0:1]
	v_cndmask_b32_e64 v26, v42, v50, s[0:1]
	v_cndmask_b32_e64 v29, v62, v104, s[0:1]
	v_cndmask_b32_e64 v28, v58, v98, s[0:1]
	v_cndmask_b32_e64 v35, v48, v56, s[0:1]
	v_cndmask_b32_e64 v34, v44, v52, s[0:1]
	v_cndmask_b32_e64 v37, v64, v108, s[0:1]
	v_cndmask_b32_e64 v36, v60, v102, s[0:1]
	v_pk_mul_f32 v[28:29], v[84:85], v[28:29]
	v_pk_mul_f32 v[26:27], v[82:83], v[26:27]
	v_mov_b32_dpp v43, v22 row_ror:2 row_mask:0xf bank_mask:0xf
	v_mov_b32_dpp v47, v23 row_ror:2 row_mask:0xf bank_mask:0xf
	v_mov_b32_dpp v59, v24 row_ror:2 row_mask:0xf bank_mask:0xf
	v_mov_b32_dpp v63, v25 row_ror:2 row_mask:0xf bank_mask:0xf
	v_pk_fma_f32 v[22:23], v[22:23], v[86:87], v[26:27]
	v_pk_fma_f32 v[24:25], v[24:25], v[88:89], v[28:29]
	v_pk_mul_f32 v[26:27], v[72:73], v[36:37]
	v_pk_mul_f32 v[28:29], v[70:71], v[34:35]
	v_cndmask_b32_e64 v39, v57, v49, s[2:3]
	v_cndmask_b32_e64 v38, v53, v45, s[2:3]
	v_cndmask_b32_e64 v41, v109, v65, s[2:3]
	v_cndmask_b32_e64 v40, v103, v61, s[2:3]
	v_pk_fma_f32 v[18:19], v[18:19], v[74:75], v[28:29]
	v_pk_fma_f32 v[20:21], v[20:21], v[76:77], v[26:27]
	v_pk_fma_f32 v[18:19], v[66:67], v[38:39], v[18:19]
	v_pk_fma_f32 v[20:21], v[68:69], v[40:41], v[20:21]
	v_mul_f32_e32 v26, 0xbfb8aa3b, v18
	v_mul_f32_e32 v27, 0xbfb8aa3b, v19
	v_mul_f32_e32 v28, 0xbfb8aa3b, v20
	v_mul_f32_e32 v29, 0xbfb8aa3b, v21
	v_exp_f32_e32 v26, v26
	v_exp_f32_e32 v27, v27
	v_exp_f32_e32 v28, v28
	v_exp_f32_e32 v29, v29
	v_add_f32_e32 v26, 1.0, v26
	v_add_f32_e32 v27, 1.0, v27
	v_add_f32_e32 v28, 1.0, v28
	v_add_f32_e32 v29, 1.0, v29
	v_rcp_f32_e32 v26, v26
	v_rcp_f32_e32 v27, v27
	v_rcp_f32_e32 v28, v28
	v_rcp_f32_e32 v29, v29
	v_mov_b32_dpp v34, v14 row_ror:1 row_mask:0xf bank_mask:0xf
	v_mov_b32_dpp v38, v15 row_ror:1 row_mask:0xf bank_mask:0xf
	v_mov_b32_dpp v50, v16 row_ror:1 row_mask:0xf bank_mask:0xf
	v_mov_b32_dpp v54, v17 row_ror:1 row_mask:0xf bank_mask:0xf
	v_cndmask_b32_e64 v31, v55, v47, s[2:3]
	v_cndmask_b32_e64 v30, v51, v43, s[2:3]
	v_cndmask_b32_e64 v33, v105, v63, s[2:3]
	v_cndmask_b32_e64 v32, v99, v59, s[2:3]
	v_mov_b32_dpp v36, v10 row_ror:1 row_mask:0xf bank_mask:0xf
	v_mov_b32_dpp v40, v11 row_ror:1 row_mask:0xf bank_mask:0xf
	v_mov_b32_dpp v52, v12 row_ror:1 row_mask:0xf bank_mask:0xf
	v_mov_b32_dpp v56, v13 row_ror:1 row_mask:0xf bank_mask:0xf
	v_pk_fma_f32 v[24:25], v[80:81], v[32:33], v[24:25]
	v_pk_fma_f32 v[22:23], v[78:79], v[30:31], v[22:23]
	v_pk_mul_f32 v[18:19], v[18:19], v[26:27]
	v_pk_mul_f32 v[20:21], v[20:21], v[28:29]
	v_pk_mul_f32 v[18:19], v[22:23], v[18:19]
	v_pk_mul_f32 v[20:21], v[24:25], v[20:21]
	v_mov_b32_dpp v37, v10 row_ror:2 row_mask:0xf bank_mask:0xf
	v_mov_b32_dpp v41, v11 row_ror:2 row_mask:0xf bank_mask:0xf
	v_mov_b32_dpp v53, v12 row_ror:2 row_mask:0xf bank_mask:0xf
	v_mov_b32_dpp v57, v13 row_ror:2 row_mask:0xf bank_mask:0xf
	v_cvt_pk_bf16_f32 v18, v18, v19
	v_cvt_pk_bf16_f32 v19, v20, v21
	global_store_dwordx2 v[94:95], v[18:19], off offset:8
	v_cndmask_b32_e64 v19, v38, v46, s[0:1]
	v_cndmask_b32_e64 v18, v34, v42, s[0:1]
	v_cndmask_b32_e64 v21, v54, v62, s[0:1]
	v_cndmask_b32_e64 v20, v50, v58, s[0:1]
	v_cndmask_b32_e64 v27, v40, v48, s[0:1]
	v_cndmask_b32_e64 v26, v36, v44, s[0:1]
	v_cndmask_b32_e64 v29, v56, v64, s[0:1]
	v_cndmask_b32_e64 v28, v52, v60, s[0:1]
	v_pk_mul_f32 v[20:21], v[84:85], v[20:21]
	v_pk_mul_f32 v[18:19], v[82:83], v[18:19]
	v_mov_b32_dpp v35, v14 row_ror:2 row_mask:0xf bank_mask:0xf
	v_mov_b32_dpp v39, v15 row_ror:2 row_mask:0xf bank_mask:0xf
	v_mov_b32_dpp v51, v16 row_ror:2 row_mask:0xf bank_mask:0xf
	v_mov_b32_dpp v55, v17 row_ror:2 row_mask:0xf bank_mask:0xf
	v_pk_fma_f32 v[14:15], v[14:15], v[86:87], v[18:19]
	v_pk_fma_f32 v[16:17], v[16:17], v[88:89], v[20:21]
	v_pk_mul_f32 v[18:19], v[72:73], v[28:29]
	v_pk_mul_f32 v[20:21], v[70:71], v[26:27]
	v_cndmask_b32_e64 v31, v49, v41, s[2:3]
	v_cndmask_b32_e64 v30, v45, v37, s[2:3]
	v_cndmask_b32_e64 v33, v65, v57, s[2:3]
; __device__ __forceinline__ unsigned cvt_pk_bf16(float lo, float hi) { f32x2_t f = {lo, hi}; bf16x2_t v = __builtin_convertvector(f, bf16x2_t); return __builtin_bit_cast(unsigned, v); }
; __device__ __forceinline__ float sigmoidf_(float x) { return __builtin_amdgcn_rcpf(1.0f + __expf(-x)); }
; #define SHI(lane, v, src) shfl_idx(lane, (v), (src))
;     __device__ __forceinline__ void operator()(const f32x4 (&acc)[2][2][4][2], const Unit& u, int wr, int wc, int fr, int fq) const {
;     ...
;             for (int q = 0; q < 8; ++q) {
;                 const int ai = q >> 2, m = q & 3;
;                 const f32x4 av = acc[ai][0][m][n], ag = acc[ai][1][m][n];
;                 f32x4 rv1, rv2, rg1, rg2;
; #pragma unroll
;                 for (int j = 0; j < 4; ++j) { rv1[j] = SHI(lane, av[j], src1); rv2[j] = SHI(lane, av[j], src2); rg1[j] = SHI(lane, ag[j], src1); rg2[j] = SHI(lane, ag[j], src2); }
;                 const f32x4 sv1 = fr >= 1 ? rv1 : pv1, sv2 = fr >= 2 ? rv2 : pv2, sg1 = fr >= 1 ? rg1 : pg1, sg2 = fr >= 2 ? rg2 : pg2;
;                 const f32x4 ov = wv[2] * av + wv[1] * sv1 + wv[0] * sv2;
;                 const f32x4 og = wg[2] * ag + wg[1] * sg1 + wg[0] * sg2;
;                 u32x2 w;
;                 w.x = cvt_pk_bf16(og[0] * sigmoidf_(og[0]) * ov[0], og[1] * sigmoidf_(og[1]) * ov[1]);
;                 w.y = cvt_pk_bf16(og[2] * sigmoidf_(og[2]) * ov[2], og[3] * sigmoidf_(og[3]) * ov[3]);
;                 *(u32x2*)(act + (size_t)(tok0 + q * 16) * DFF + ch) = w;
;                 if (q == 0 && fr < 2) { float* hp = halo + ((size_t)seg * 4 + fr) * NUP + ch; *(f32x4*)hp = av; *(f32x4*)(hp + DFF) = ag; }
;                 if (q == 7 && fr >= 14) { float* hp = halo + ((size_t)seg * 4 + (fr - 12)) * NUP + ch; *(f32x4*)hp = av; *(f32x4*)(hp + DFF) = ag; }
;                 pv1 = rv1; pv2 = rv2; pg1 = rg1; pg2 = rg2;
;             }
	v_cndmask_b32_e64 v32, v61, v53, s[2:3]
	v_pk_fma_f32 v[10:11], v[10:11], v[74:75], v[20:21]
	v_pk_fma_f32 v[12:13], v[12:13], v[76:77], v[18:19]
	v_pk_fma_f32 v[10:11], v[66:67], v[30:31], v[10:11]
	v_pk_fma_f32 v[12:13], v[68:69], v[32:33], v[12:13]
	v_mul_f32_e32 v18, 0xbfb8aa3b, v10
	v_mul_f32_e32 v19, 0xbfb8aa3b, v11
	v_mul_f32_e32 v20, 0xbfb8aa3b, v12
	v_mul_f32_e32 v21, 0xbfb8aa3b, v13
	v_exp_f32_e32 v18, v18
	v_exp_f32_e32 v19, v19
	v_exp_f32_e32 v20, v20
	v_exp_f32_e32 v21, v21
	v_add_f32_e32 v18, 1.0, v18
	v_add_f32_e32 v19, 1.0, v19
	v_add_f32_e32 v20, 1.0, v20
	v_add_f32_e32 v21, 1.0, v21
	v_rcp_f32_e32 v18, v18
	v_rcp_f32_e32 v19, v19
	v_rcp_f32_e32 v20, v20
	v_rcp_f32_e32 v21, v21
	v_cndmask_b32_e64 v23, v47, v39, s[2:3]
	v_cndmask_b32_e64 v22, v43, v35, s[2:3]
	v_cndmask_b32_e64 v25, v63, v55, s[2:3]
	v_cndmask_b32_e64 v24, v59, v51, s[2:3]
	v_pk_fma_f32 v[16:17], v[80:81], v[24:25], v[16:17]
	v_pk_fma_f32 v[14:15], v[78:79], v[22:23], v[14:15]
	v_pk_mul_f32 v[10:11], v[10:11], v[18:19]
	v_pk_mul_f32 v[12:13], v[12:13], v[20:21]
	v_pk_mul_f32 v[10:11], v[14:15], v[10:11]
	v_pk_mul_f32 v[12:13], v[16:17], v[12:13]
	v_cvt_pk_bf16_f32 v10, v10, v11
	v_cvt_pk_bf16_f32 v11, v12, v13
	global_store_dwordx2 v[96:97], v[10:11], off offset:8
	v_mov_b32_dpp v10, v6 row_ror:1 row_mask:0xf bank_mask:0xf
	v_mov_b32_dpp v11, v7 row_ror:1 row_mask:0xf bank_mask:0xf
	v_mov_b32_dpp v12, v8 row_ror:1 row_mask:0xf bank_mask:0xf
	v_mov_b32_dpp v13, v9 row_ror:1 row_mask:0xf bank_mask:0xf
	v_mov_b32_dpp v14, v6 row_ror:2 row_mask:0xf bank_mask:0xf
	v_mov_b32_dpp v18, v2 row_ror:1 row_mask:0xf bank_mask:0xf
	v_mov_b32_dpp v15, v7 row_ror:2 row_mask:0xf bank_mask:0xf
	v_mov_b32_dpp v19, v3 row_ror:1 row_mask:0xf bank_mask:0xf
	v_mov_b32_dpp v16, v8 row_ror:2 row_mask:0xf bank_mask:0xf
	v_mov_b32_dpp v20, v4 row_ror:1 row_mask:0xf bank_mask:0xf
	v_mov_b32_dpp v17, v9 row_ror:2 row_mask:0xf bank_mask:0xf
	v_mov_b32_dpp v21, v5 row_ror:1 row_mask:0xf bank_mask:0xf
	v_mov_b32_dpp v22, v2 row_ror:2 row_mask:0xf bank_mask:0xf
	v_mov_b32_dpp v23, v3 row_ror:2 row_mask:0xf bank_mask:0xf
	v_mov_b32_dpp v24, v4 row_ror:2 row_mask:0xf bank_mask:0xf
	v_mov_b32_dpp v25, v5 row_ror:2 row_mask:0xf bank_mask:0xf
	v_cndmask_b32_e64 v11, v11, v38, s[0:1]
	v_cndmask_b32_e64 v10, v10, v34, s[0:1]
	v_cndmask_b32_e64 v13, v13, v54, s[0:1]
	v_cndmask_b32_e64 v12, v12, v50, s[0:1]
	v_pk_mul_f32 v[12:13], v[84:85], v[12:13]
	v_pk_mul_f32 v[10:11], v[82:83], v[10:11]
	v_cndmask_b32_e64 v15, v39, v15, s[2:3]
	v_cndmask_b32_e64 v14, v35, v14, s[2:3]
	v_cndmask_b32_e64 v17, v55, v17, s[2:3]
	v_cndmask_b32_e64 v16, v51, v16, s[2:3]
	v_cndmask_b32_e64 v19, v19, v40, s[0:1]
	v_cndmask_b32_e64 v18, v18, v36, s[0:1]
	v_cndmask_b32_e64 v21, v21, v56, s[0:1]
	v_cndmask_b32_e64 v20, v20, v52, s[0:1]
	v_pk_fma_f32 v[10:11], v[6:7], v[86:87], v[10:11]
	v_pk_fma_f32 v[12:13], v[8:9], v[88:89], v[12:13]
	v_pk_fma_f32 v[10:11], v[78:79], v[14:15], v[10:11]
	v_pk_fma_f32 v[12:13], v[80:81], v[16:17], v[12:13]
	v_pk_mul_f32 v[14:15], v[72:73], v[20:21]
	v_pk_mul_f32 v[16:17], v[70:71], v[18:19]
	v_cndmask_b32_e64 v23, v41, v23, s[2:3]
	v_cndmask_b32_e64 v22, v37, v22, s[2:3]
	v_cndmask_b32_e64 v25, v57, v25, s[2:3]
	v_cndmask_b32_e64 v24, v53, v24, s[2:3]
	v_pk_fma_f32 v[16:17], v[2:3], v[74:75], v[16:17]
	v_pk_fma_f32 v[14:15], v[4:5], v[76:77], v[14:15]
	v_pk_fma_f32 v[16:17], v[66:67], v[22:23], v[16:17]
	v_pk_fma_f32 v[14:15], v[68:69], v[24:25], v[14:15]
	v_mul_f32_e32 v18, 0xbfb8aa3b, v16
	v_mul_f32_e32 v19, 0xbfb8aa3b, v17
	v_mul_f32_e32 v20, 0xbfb8aa3b, v14
	v_mul_f32_e32 v21, 0xbfb8aa3b, v15
	v_exp_f32_e32 v18, v18
	v_exp_f32_e32 v19, v19
	v_exp_f32_e32 v20, v20
	v_exp_f32_e32 v21, v21
	v_add_f32_e32 v18, 1.0, v18
	v_add_f32_e32 v19, 1.0, v19
	v_add_f32_e32 v20, 1.0, v20
	v_add_f32_e32 v21, 1.0, v21
	v_rcp_f32_e32 v18, v18
	v_rcp_f32_e32 v19, v19
	v_rcp_f32_e32 v20, v20
	v_rcp_f32_e32 v21, v21
	v_pk_mul_f32 v[16:17], v[16:17], v[18:19]
	s_nop 0
	v_pk_mul_f32 v[10:11], v[10:11], v[16:17]
	v_pk_mul_f32 v[14:15], v[14:15], v[20:21]
	v_cvt_pk_bf16_f32 v10, v10, v11
	v_pk_mul_f32 v[12:13], v[12:13], v[14:15]
	s_nop 0
	v_cvt_pk_bf16_f32 v11, v12, v13
	global_store_dwordx2 v[100:101], v[10:11], off offset:8
	s_and_saveexec_b64 s[76:77], s[6:7]
	s_cbranch_execz .LBB0_615
	global_store_dwordx4 v[90:91], v[6:9], off offset:16
	s_nop 1
	v_add_co_u32_e32 v6, vcc, 0x5000, v90
	s_nop 1
	v_addc_co_u32_e32 v7, vcc, 0, v91, vcc
	global_store_dwordx4 v[6:7], v[2:5], off offset:2064
	s_branch .LBB0_615

; __device__ __forceinline__ int otid(int wv) { int t = (wv << 6) | (int)__builtin_amdgcn_mbcnt_hi(~0u, __builtin_amdgcn_mbcnt_lo(~0u, 0u)); asm volatile("" : "+v"(t)); return t; }
; #define PG8_WAIT_V(n) asm volatile("s_waitcnt vmcnt(" #n ")" ::: "memory")
; #define PG8_BAR __builtin_amdgcn_s_barrier()
; template <class Epi, class Sched, bool AREMAP>
; __device__ __forceinline__ void gemm_phase(LAS unsigned char* lds, const Gemm g, const Sched& S, const Epi& E, int wv) {
;     ...
;     PG8_WAIT_V(0);
;     if (wr == 0) PG8_BAR;
;     PG8_BAR;
; __device__ __forceinline__ void grid_bar(unsigned* ctr, unsigned& target, int G, int wv) {
;     asm volatile("s_waitcnt vmcnt(0) lgkmcnt(0)" ::: "memory");
;     __syncthreads();
;     target = (unsigned)__builtin_amdgcn_readfirstlane((int)(target + (unsigned)G));
;     if (otid(wv) == 0) {
;         __builtin_amdgcn_fence(__ATOMIC_RELEASE, "agent");
;         asm volatile("s_waitcnt vmcnt(0)" ::: "memory");
;         __hip_atomic_fetch_add(ctr, 1u, __ATOMIC_RELAXED, __HIP_MEMORY_SCOPE_AGENT);
;         while (__hip_atomic_load(ctr, __ATOMIC_RELAXED, __HIP_MEMORY_SCOPE_AGENT) < target) __builtin_amdgcn_s_sleep(1);
.LBB0_631:
	s_setprio 0
	s_waitcnt vmcnt(0) lgkmcnt(0)
	v_mov_b32_e32 v1, v236
	s_barrier
	s_add_i32 s10, s20, s33
	s_nop 0
	v_cmp_eq_u32_e32 vcc, 0, v1
	s_and_saveexec_b64 s[0:1], vcc
	v_readlane_b32 s68, v255, 33
	v_readlane_b32 s72, v255, 35
	s_mov_b64 s[52:53], 0x41000
	v_readlane_b32 s69, v255, 34
	v_readlane_b32 s73, v255, 36
	s_cbranch_execz .LBB0_637
	s_mov_b64 s[2:3], exec
	buffer_wbl2 sc1
	s_waitcnt vmcnt(0)
	v_mbcnt_lo_u32_b32 v1, s2, 0
	v_mbcnt_hi_u32_b32 v1, s3, v1
	v_cmp_eq_u32_e32 vcc, 0, v1
	s_and_saveexec_b64 s[4:5], vcc
	s_cbranch_execz .LBB0_634
	s_bcnt1_i32_b64 s2, s[2:3]
	v_mov_b32_e32 v1, s2
	v_readlane_b32 s2, v254, 30
	v_readlane_b32 s3, v254, 31
	s_nop 4
	global_atomic_add v0, v1, s[2:3]

; __device__ __forceinline__ int otid(int wv) { int t = (wv << 6) | (int)__builtin_amdgcn_mbcnt_hi(~0u, __builtin_amdgcn_mbcnt_lo(~0u, 0u)); asm volatile("" : "+v"(t)); return t; }
; __device__ __forceinline__ void grid_bar(unsigned* ctr, unsigned& target, int G, int wv) {
;     asm volatile("s_waitcnt vmcnt(0) lgkmcnt(0)" ::: "memory");
;     __syncthreads();
;     target = (unsigned)__builtin_amdgcn_readfirstlane((int)(target + (unsigned)G));
;     if (otid(wv) == 0) {
;         __builtin_amdgcn_fence(__ATOMIC_RELEASE, "agent");
;         asm volatile("s_waitcnt vmcnt(0)" ::: "memory");
;         __hip_atomic_fetch_add(ctr, 1u, __ATOMIC_RELAXED, __HIP_MEMORY_SCOPE_AGENT);
;         while (__hip_atomic_load(ctr, __ATOMIC_RELAXED, __HIP_MEMORY_SCOPE_AGENT) < target) __builtin_amdgcn_s_sleep(1);
.LBB0_646:
	s_or_b64 exec, exec, s[0:1]
	s_setprio 0
	s_waitcnt vmcnt(0) lgkmcnt(0)
	v_mov_b32_e32 v1, v236
	s_waitcnt lgkmcnt(0)
	s_barrier
	s_add_i32 s10, s10, s33
	s_nop 0
	v_cmp_eq_u32_e32 vcc, 0, v1
	s_and_saveexec_b64 s[0:1], vcc
	s_cbranch_execz .LBB0_652
	s_mov_b64 s[2:3], exec
	buffer_wbl2 sc1
	s_waitcnt vmcnt(0)
	v_mbcnt_lo_u32_b32 v1, s2, 0
	v_mbcnt_hi_u32_b32 v1, s3, v1
	v_cmp_eq_u32_e32 vcc, 0, v1
	s_and_saveexec_b64 s[4:5], vcc
	s_cbranch_execz .LBB0_649
	s_bcnt1_i32_b64 s2, s[2:3]
	v_mov_b32_e32 v1, s2
	v_readlane_b32 s2, v254, 30
	v_readlane_b32 s3, v254, 31
	s_nop 4
	global_atomic_add v0, v1, s[2:3]

; __device__ __forceinline__ int otid(int wv) { int t = (wv << 6) | (int)__builtin_amdgcn_mbcnt_hi(~0u, __builtin_amdgcn_mbcnt_lo(~0u, 0u)); asm volatile("" : "+v"(t)); return t; }
; __device__ __forceinline__ void grid_bar(unsigned* ctr, unsigned& target, int G, int wv) {
;     asm volatile("s_waitcnt vmcnt(0) lgkmcnt(0)" ::: "memory");
;     __syncthreads();
;     target = (unsigned)__builtin_amdgcn_readfirstlane((int)(target + (unsigned)G));
;     if (otid(wv) == 0) {
;         __builtin_amdgcn_fence(__ATOMIC_RELEASE, "agent");
;         asm volatile("s_waitcnt vmcnt(0)" ::: "memory");
;         __hip_atomic_fetch_add(ctr, 1u, __ATOMIC_RELAXED, __HIP_MEMORY_SCOPE_AGENT);
;         while (__hip_atomic_load(ctr, __ATOMIC_RELAXED, __HIP_MEMORY_SCOPE_AGENT) < target) __builtin_amdgcn_s_sleep(1);
.LBB0_713:
	s_setprio 0
	s_waitcnt vmcnt(0) lgkmcnt(0)
	v_mov_b32_e32 v1, v236
	s_waitcnt lgkmcnt(0)
	s_barrier
	s_add_i32 s22, s10, s33
	s_nop 0
	v_cmp_eq_u32_e32 vcc, 0, v1
	s_and_saveexec_b64 s[0:1], vcc
	s_cbranch_execz .LBB0_719
	s_mov_b64 s[2:3], exec
	buffer_wbl2 sc1
	s_waitcnt vmcnt(0)
	v_mbcnt_lo_u32_b32 v1, s2, 0
	v_mbcnt_hi_u32_b32 v1, s3, v1
	v_cmp_eq_u32_e32 vcc, 0, v1
	s_and_saveexec_b64 s[4:5], vcc
	s_cbranch_execz .LBB0_716
	s_bcnt1_i32_b64 s2, s[2:3]
	v_mov_b32_e32 v1, s2
	v_readlane_b32 s2, v254, 30
	v_readlane_b32 s3, v254, 31
	s_nop 4
	global_atomic_add v0, v1, s[2:3]

; __device__ __forceinline__ int otid(int wv) { int t = (wv << 6) | (int)__builtin_amdgcn_mbcnt_hi(~0u, __builtin_amdgcn_mbcnt_lo(~0u, 0u)); asm volatile("" : "+v"(t)); return t; }
; #define SEAM() do { if (ph == 0) { asm volatile("s_waitcnt vmcnt(0) lgkmcnt(0)" ::: "memory"); grid.sync(); } else grid_bar(bar_ctr, bar_target, G, wv); } while (0)
; #define SEAM() do { } while (0)
; __device__ __forceinline__ void grid_bar(unsigned* ctr, unsigned& target, int G, int wv) {
;     asm volatile("s_waitcnt vmcnt(0) lgkmcnt(0)" ::: "memory");
;     __syncthreads();
;     target = (unsigned)__builtin_amdgcn_readfirstlane((int)(target + (unsigned)G));
;     if (otid(wv) == 0) {
;         __builtin_amdgcn_fence(__ATOMIC_RELEASE, "agent");
;         asm volatile("s_waitcnt vmcnt(0)" ::: "memory");
;         __hip_atomic_fetch_add(ctr, 1u, __ATOMIC_RELAXED, __HIP_MEMORY_SCOPE_AGENT);
;         while (__hip_atomic_load(ctr, __ATOMIC_RELAXED, __HIP_MEMORY_SCOPE_AGENT) < target) __builtin_amdgcn_s_sleep(1);
; __global__ void __launch_bounds__(NTHR, 2) fwd_kernel(Params p) {
;     ...
;         if (l + 1 < DEPTH) SEAM();
.LBB0_887:
	v_readlane_b32 s0, v255, 25
	v_readlane_b32 s1, v255, 26
	s_andn2_b64 vcc, exec, s[0:1]
	s_cbranch_vccnz .LBB0_186
	s_setprio 0
	s_waitcnt vmcnt(0) lgkmcnt(0)
	v_mov_b32_e32 v1, v236
	s_barrier
	s_add_i32 s22, s22, s33
	s_nop 0
	v_cmp_eq_u32_e32 vcc, 0, v1
	s_and_saveexec_b64 s[0:1], vcc
	s_cbranch_execz .LBB0_185
	s_mov_b64 s[2:3], exec
	buffer_wbl2 sc1
	s_waitcnt vmcnt(0)
	v_mbcnt_lo_u32_b32 v1, s2, 0
	v_mbcnt_hi_u32_b32 v1, s3, v1
	v_cmp_eq_u32_e32 vcc, 0, v1
	s_and_saveexec_b64 s[4:5], vcc
	s_cbranch_execz .LBB0_891
	s_bcnt1_i32_b64 s2, s[2:3]
	v_mov_b32_e32 v1, s2
	v_readlane_b32 s2, v254, 30
	v_readlane_b32 s3, v254, 31
	s_nop 4
	global_atomic_add v0, v1, s[2:3]
